# stack3 + sc1 (agent-scope write-through) on all four GEMM epilogue stores
# baseline (speedup 1.0000x reference)
; __device__ __forceinline__ unsigned cvt_pk_bf16(float lo, float hi) { unsigned r; asm volatile("v_cvt_pk_bf16_f32 %0, %1, %2" : "=v"(r) : "v"(lo), "v"(hi)); return r; }
;     __device__ __forceinline__ void operator()(const f32x4 (&acc)[2][2][4][2], const Unit& u, int wr, int wc, int fr, int fq, const float (&rsv)[8]) const {
;         const int row0 = u.pm * BM + wr * 64 + fr, col0 = u.pn * BM + wc * 32 + 8 * fq;
;         const bool isq = (u.pn < 2) || (u.pn == 6) || (u.pn == 7);
;         const float sc = isq ? QSCALE : 1.f;
;         const bool rotw = (u.pn < 4) && ((wc & 1) == 0);
;         const float sgn = (fq == 0) ? -1.f : 1.f; const bool rotl = fq < 2; const int pidx = (((fq ^ 1) << 4) | fr) << 2;
; #pragma unroll
;         for (int ai = 0; ai < 2; ++ai)
; #pragma unroll
;             for (int m = 0; m < 4; ++m) { const int row = row0 + ai * HALF + m * 16; bf16_t* rowp = O + (size_t)row * 3072 + col0; const float scr_ = sc * rsv[ai * 4 + m];
;                 f32x4 c0 = {1.f, 1.f, 1.f, 1.f}, c1 = c0, s0 = {0.f, 0.f, 0.f, 0.f}, s1 = s0;
;                 if (rotw) { const f32x4* rp = (const f32x4*)(rot + (size_t)row * 16); c0 = rp[0]; c1 = rp[1]; s0 = rp[2]; s1 = rp[3]; }
; #pragma unroll
;                 for (int bj = 0; bj < 2; ++bj) { f32x4 v0 = acc[ai][bj][m][0], v1 = acc[ai][bj][m][1];
;                     if (rotw) { f32x4 p0, p1;
; #pragma unroll
;                         for (int j = 0; j < 4; ++j) { const float a0 = v0[j], a1 = v1[j]; p0[j] = __int_as_float(__builtin_amdgcn_ds_bpermute(pidx, __float_as_int(a0))); p1[j] = __int_as_float(__builtin_amdgcn_ds_bpermute(pidx, __float_as_int(a1))); }
;                         if (rotl) { v0 = v0 * c0 + (p0 * s0) * sgn; v1 = v1 * c1 + (p1 * s1) * sgn; } }
;                     v0 = v0 * scr_; v1 = v1 * scr_; u32x4 w; w.x = cvt_pk_bf16(v0[0], v0[1]); w.y = cvt_pk_bf16(v0[2], v0[3]); w.z = cvt_pk_bf16(v1[0], v1[1]); w.w = cvt_pk_bf16(v1[2], v1[3]);
;                     *(u32x4*)(rowp + bj * HALF) = w; } }
.LBB0_101:
	s_cmp_lt_i32 s76, 2
	s_cselect_b64 s[42:43], -1, 0
	s_and_b32 s11, s76, -2
	s_cmp_eq_u32 s11, 6
	s_cselect_b64 s[58:59], -1, 0
	s_or_b64 vcc, s[42:43], s[58:59]
	v_cndmask_b32_e32 v161, 1.0, v238, vcc
	s_waitcnt lgkmcnt(0)
	v_lshl_or_b32 v162, s76, 8, v172
	v_mov_b64_e32 v[164:165], s[14:15]
	s_waitcnt vmcnt(8)
	v_mul_f32_e32 v166, v161, v182
	v_ashrrev_i32_e32 v163, 31, v162
	v_mad_i64_i32 v[164:165], s[42:43], v160, s97, v[164:165]
	v_lshl_add_u64 v[164:165], v[162:163], 1, v[164:165]
	v_pk_mul_f32 v[168:169], v[166:167], v[124:125] op_sel_hi:[0,1]
	v_pk_mul_f32 v[124:125], v[166:167], v[122:123] op_sel_hi:[0,1]
	s_and_b64 vcc, exec, s[6:7]
	v_pk_mul_f32 v[128:129], v[166:167], v[128:129] op_sel_hi:[0,1]
	v_pk_mul_f32 v[126:127], v[166:167], v[126:127] op_sel_hi:[0,1]
	v_cvt_pk_bf16_f32 v122, v126, v127
	v_cvt_pk_bf16_f32 v123, v128, v129
	v_cvt_pk_bf16_f32 v124, v124, v125
	v_cvt_pk_bf16_f32 v125, v168, v169
	v_subrev_u32_e32 v239, s14, v164
	global_store_dwordx4 v239, v[122:125], s[14:15] sc1
	s_cbranch_vccnz .LBB0_105
	ds_bpermute_b32 v126, v173, v118
	ds_bpermute_b32 v122, v173, v114
	ds_bpermute_b32 v127, v173, v119
	ds_bpermute_b32 v123, v173, v115
	ds_bpermute_b32 v128, v173, v120
	ds_bpermute_b32 v124, v173, v116
	ds_bpermute_b32 v129, v173, v121
	ds_bpermute_b32 v125, v173, v117
	s_and_saveexec_b64 s[76:77], s[8:9]
	s_cbranch_execz .LBB0_104
	s_waitcnt lgkmcnt(1)
	v_pk_mul_f32 v[128:129], v[144:145], v[128:129]
	v_pk_mul_f32 v[126:127], v[142:143], v[126:127]
	s_waitcnt lgkmcnt(0)
	v_pk_mul_f32 v[124:125], v[140:141], v[124:125]
	v_pk_mul_f32 v[122:123], v[138:139], v[122:123]
	v_pk_mul_f32 v[128:129], v[154:155], v[128:129]
	v_pk_mul_f32 v[126:127], v[152:153], v[126:127]
	v_pk_mul_f32 v[124:125], v[154:155], v[124:125]
	v_pk_mul_f32 v[122:123], v[152:153], v[122:123]
	v_pk_fma_f32 v[120:121], v[120:121], v[136:137], v[128:129]
	v_pk_fma_f32 v[118:119], v[118:119], v[134:135], v[126:127]
	v_pk_fma_f32 v[116:117], v[116:117], v[132:133], v[124:125]
	v_pk_fma_f32 v[114:115], v[114:115], v[130:131], v[122:123]

; __device__ __forceinline__ unsigned cvt_pk_bf16(float lo, float hi) { unsigned r; asm volatile("v_cvt_pk_bf16_f32 %0, %1, %2" : "=v"(r) : "v"(lo), "v"(hi)); return r; }
;     __device__ __forceinline__ void operator()(const f32x4 (&acc)[2][2][4][2], const Unit& u, int wr, int wc, int fr, int fq, const float (&rsv)[8]) const {
;     ...
;             for (int m = 0; m < 4; ++m) { const int row = row0 + ai * HALF + m * 16; bf16_t* rowp = O + (size_t)row * 3072 + col0; const float scr_ = sc * rsv[ai * 4 + m];
;                 f32x4 c0 = {1.f, 1.f, 1.f, 1.f}, c1 = c0, s0 = {0.f, 0.f, 0.f, 0.f}, s1 = s0;
;                 if (rotw) { const f32x4* rp = (const f32x4*)(rot + (size_t)row * 16); c0 = rp[0]; c1 = rp[1]; s0 = rp[2]; s1 = rp[3]; }
; #pragma unroll
;                 for (int bj = 0; bj < 2; ++bj) { f32x4 v0 = acc[ai][bj][m][0], v1 = acc[ai][bj][m][1];
;                     if (rotw) { f32x4 p0, p1;
; #pragma unroll
;                         for (int j = 0; j < 4; ++j) { const float a0 = v0[j], a1 = v1[j]; p0[j] = __int_as_float(__builtin_amdgcn_ds_bpermute(pidx, __float_as_int(a0))); p1[j] = __int_as_float(__builtin_amdgcn_ds_bpermute(pidx, __float_as_int(a1))); }
;                         if (rotl) { v0 = v0 * c0 + (p0 * s0) * sgn; v1 = v1 * c1 + (p1 * s1) * sgn; } }
;                     v0 = v0 * scr_; v1 = v1 * scr_; u32x4 w; w.x = cvt_pk_bf16(v0[0], v0[1]); w.y = cvt_pk_bf16(v0[2], v0[3]); w.z = cvt_pk_bf16(v1[0], v1[1]); w.w = cvt_pk_bf16(v1[2], v1[3]);
;                     *(u32x4*)(rowp + bj * HALF) = w; } }
.LBB0_105:
	v_mov_b32_e32 v167, v166
	s_waitcnt lgkmcnt(6)
	v_mov_b32_e32 v122, v166
	s_waitcnt lgkmcnt(4)
	v_mov_b32_e32 v123, v166
	v_or_b32_e32 v130, 16, v160
	v_pk_mul_f32 v[120:121], v[122:123], v[120:121]
	v_pk_mul_f32 v[122:123], v[122:123], v[116:117]
	v_pk_mul_f32 v[116:117], v[166:167], v[114:115]
	s_and_b64 vcc, exec, s[6:7]
	v_ashrrev_i32_e32 v131, 31, v130
	v_pk_mul_f32 v[118:119], v[166:167], v[118:119]
	s_nop 0
	v_cvt_pk_bf16_f32 v114, v118, v119
	v_cvt_pk_bf16_f32 v115, v120, v121
	v_cvt_pk_bf16_f32 v116, v116, v117
	v_cvt_pk_bf16_f32 v117, v122, v123
	v_subrev_u32_e32 v239, s14, v164
	global_store_dwordx4 v239, v[114:117], s[14:15] offset:256 sc1
	s_cbranch_vccnz .LBB0_107
	s_nop 0
	v_lshlrev_b64 v[114:115], 6, v[130:131]
	v_lshl_add_u64 v[122:123], s[16:17], 0, v[114:115]
	global_load_dwordx4 v[118:121], v[122:123], off
	global_load_dwordx4 v[114:117], v[122:123], off offset:16
	s_waitcnt lgkmcnt(1)
	global_load_dwordx4 v[126:129], v[122:123], off offset:32
	s_waitcnt lgkmcnt(0)
	global_load_dwordx4 v[122:125], v[122:123], off offset:48
	s_and_b64 vcc, exec, s[6:7]
	s_cbranch_vccz .LBB0_108
	s_branch .LBB0_111

; __device__ __forceinline__ unsigned cvt_pk_bf16(float lo, float hi) { unsigned r; asm volatile("v_cvt_pk_bf16_f32 %0, %1, %2" : "=v"(r) : "v"(lo), "v"(hi)); return r; }
;     __device__ __forceinline__ void operator()(const f32x4 (&acc)[2][2][4][2], const Unit& u, int wr, int wc, int fr, int fq, const float (&rsv)[8]) const {
;     ...
;             for (int m = 0; m < 4; ++m) { const int row = row0 + ai * HALF + m * 16; bf16_t* rowp = O + (size_t)row * 3072 + col0; const float scr_ = sc * rsv[ai * 4 + m];
;                 f32x4 c0 = {1.f, 1.f, 1.f, 1.f}, c1 = c0, s0 = {0.f, 0.f, 0.f, 0.f}, s1 = s0;
;                 if (rotw) { const f32x4* rp = (const f32x4*)(rot + (size_t)row * 16); c0 = rp[0]; c1 = rp[1]; s0 = rp[2]; s1 = rp[3]; }
; #pragma unroll
;                 for (int bj = 0; bj < 2; ++bj) { f32x4 v0 = acc[ai][bj][m][0], v1 = acc[ai][bj][m][1];
;                     if (rotw) { f32x4 p0, p1;
; #pragma unroll
;                         for (int j = 0; j < 4; ++j) { const float a0 = v0[j], a1 = v1[j]; p0[j] = __int_as_float(__builtin_amdgcn_ds_bpermute(pidx, __float_as_int(a0))); p1[j] = __int_as_float(__builtin_amdgcn_ds_bpermute(pidx, __float_as_int(a1))); }
;                         if (rotl) { v0 = v0 * c0 + (p0 * s0) * sgn; v1 = v1 * c1 + (p1 * s1) * sgn; } }
;                     v0 = v0 * scr_; v1 = v1 * scr_; u32x4 w; w.x = cvt_pk_bf16(v0[0], v0[1]); w.y = cvt_pk_bf16(v0[2], v0[3]); w.z = cvt_pk_bf16(v1[0], v1[1]); w.w = cvt_pk_bf16(v1[2], v1[3]);
;                     *(u32x4*)(rowp + bj * HALF) = w; } }
.LBB0_111:
	s_waitcnt lgkmcnt(0)
	v_mov_b64_e32 v[134:135], s[14:15]
	v_mul_f32_e32 v132, v161, v181
	v_mad_i64_i32 v[130:131], s[42:43], v130, s97, v[134:135]
	v_lshl_add_u64 v[130:131], v[162:163], 1, v[130:131]
	v_pk_mul_f32 v[134:135], v[132:133], v[108:109] op_sel_hi:[0,1]
	v_pk_mul_f32 v[108:109], v[132:133], v[106:107] op_sel_hi:[0,1]
	s_and_b64 vcc, exec, s[6:7]
	v_pk_mul_f32 v[112:113], v[132:133], v[112:113] op_sel_hi:[0,1]
	v_pk_mul_f32 v[110:111], v[132:133], v[110:111] op_sel_hi:[0,1]
	v_cvt_pk_bf16_f32 v106, v110, v111
	v_cvt_pk_bf16_f32 v107, v112, v113
	v_cvt_pk_bf16_f32 v108, v108, v109
	v_cvt_pk_bf16_f32 v109, v134, v135
	v_subrev_u32_e32 v239, s14, v130
	global_store_dwordx4 v239, v[106:109], s[14:15] sc1
	s_cbranch_vccnz .LBB0_115
	ds_bpermute_b32 v110, v173, v102
	ds_bpermute_b32 v106, v173, v98
	ds_bpermute_b32 v111, v173, v103
	ds_bpermute_b32 v107, v173, v99
	ds_bpermute_b32 v112, v173, v104
	ds_bpermute_b32 v108, v173, v100
	ds_bpermute_b32 v113, v173, v105
	ds_bpermute_b32 v109, v173, v101
	s_and_saveexec_b64 s[76:77], s[8:9]
	s_cbranch_execz .LBB0_114
	s_waitcnt vmcnt(2) lgkmcnt(1)
	v_pk_mul_f32 v[112:113], v[128:129], v[112:113]
	v_pk_mul_f32 v[110:111], v[126:127], v[110:111]
	s_waitcnt vmcnt(1) lgkmcnt(0)
	v_pk_mul_f32 v[108:109], v[124:125], v[108:109]
	v_pk_mul_f32 v[106:107], v[122:123], v[106:107]
	v_pk_mul_f32 v[112:113], v[154:155], v[112:113]
	v_pk_mul_f32 v[110:111], v[152:153], v[110:111]
	v_pk_mul_f32 v[108:109], v[154:155], v[108:109]
	v_pk_mul_f32 v[106:107], v[152:153], v[106:107]
	v_pk_fma_f32 v[104:105], v[104:105], v[120:121], v[112:113]
	v_pk_fma_f32 v[102:103], v[102:103], v[118:119], v[110:111]
	v_pk_fma_f32 v[100:101], v[100:101], v[116:117], v[108:109]
	v_pk_fma_f32 v[98:99], v[98:99], v[114:115], v[106:107]

; __device__ __forceinline__ unsigned cvt_pk_bf16(float lo, float hi) { unsigned r; asm volatile("v_cvt_pk_bf16_f32 %0, %1, %2" : "=v"(r) : "v"(lo), "v"(hi)); return r; }
;     __device__ __forceinline__ void operator()(const f32x4 (&acc)[2][2][4][2], const Unit& u, int wr, int wc, int fr, int fq, const float (&rsv)[8]) const {
;     ...
;             for (int m = 0; m < 4; ++m) { const int row = row0 + ai * HALF + m * 16; bf16_t* rowp = O + (size_t)row * 3072 + col0; const float scr_ = sc * rsv[ai * 4 + m];
;                 f32x4 c0 = {1.f, 1.f, 1.f, 1.f}, c1 = c0, s0 = {0.f, 0.f, 0.f, 0.f}, s1 = s0;
;                 if (rotw) { const f32x4* rp = (const f32x4*)(rot + (size_t)row * 16); c0 = rp[0]; c1 = rp[1]; s0 = rp[2]; s1 = rp[3]; }
; #pragma unroll
;                 for (int bj = 0; bj < 2; ++bj) { f32x4 v0 = acc[ai][bj][m][0], v1 = acc[ai][bj][m][1];
;                     if (rotw) { f32x4 p0, p1;
; #pragma unroll
;                         for (int j = 0; j < 4; ++j) { const float a0 = v0[j], a1 = v1[j]; p0[j] = __int_as_float(__builtin_amdgcn_ds_bpermute(pidx, __float_as_int(a0))); p1[j] = __int_as_float(__builtin_amdgcn_ds_bpermute(pidx, __float_as_int(a1))); }
;                         if (rotl) { v0 = v0 * c0 + (p0 * s0) * sgn; v1 = v1 * c1 + (p1 * s1) * sgn; } }
;                     v0 = v0 * scr_; v1 = v1 * scr_; u32x4 w; w.x = cvt_pk_bf16(v0[0], v0[1]); w.y = cvt_pk_bf16(v0[2], v0[3]); w.z = cvt_pk_bf16(v1[0], v1[1]); w.w = cvt_pk_bf16(v1[2], v1[3]);
;                     *(u32x4*)(rowp + bj * HALF) = w; } }
.LBB0_115:
	v_mov_b32_e32 v133, v132
	s_waitcnt lgkmcnt(6)
	v_mov_b32_e32 v106, v132
	s_waitcnt lgkmcnt(4)
	v_mov_b32_e32 v107, v132
	s_waitcnt vmcnt(3)
	v_or_b32_e32 v114, 32, v160
	v_pk_mul_f32 v[104:105], v[106:107], v[104:105]
	v_pk_mul_f32 v[106:107], v[106:107], v[100:101]
	v_pk_mul_f32 v[100:101], v[132:133], v[98:99]
	s_and_b64 vcc, exec, s[6:7]
	v_ashrrev_i32_e32 v115, 31, v114
	v_pk_mul_f32 v[102:103], v[132:133], v[102:103]
	s_nop 0
	v_cvt_pk_bf16_f32 v98, v102, v103
	v_cvt_pk_bf16_f32 v99, v104, v105
	v_cvt_pk_bf16_f32 v100, v100, v101
	v_cvt_pk_bf16_f32 v101, v106, v107
	v_subrev_u32_e32 v239, s14, v130
	global_store_dwordx4 v239, v[98:101], s[14:15] offset:256 sc1
	s_cbranch_vccnz .LBB0_117
	s_nop 0
	v_lshlrev_b64 v[98:99], 6, v[114:115]
	v_lshl_add_u64 v[106:107], s[16:17], 0, v[98:99]
	global_load_dwordx4 v[102:105], v[106:107], off
	global_load_dwordx4 v[98:101], v[106:107], off offset:16
	s_waitcnt lgkmcnt(1)
	global_load_dwordx4 v[110:113], v[106:107], off offset:32
	s_waitcnt lgkmcnt(0)
	global_load_dwordx4 v[106:109], v[106:107], off offset:48
	s_and_b64 vcc, exec, s[6:7]
	s_cbranch_vccz .LBB0_118
	s_branch .LBB0_121

; __device__ __forceinline__ unsigned cvt_pk_bf16(float lo, float hi) { unsigned r; asm volatile("v_cvt_pk_bf16_f32 %0, %1, %2" : "=v"(r) : "v"(lo), "v"(hi)); return r; }
;     __device__ __forceinline__ void operator()(const f32x4 (&acc)[2][2][4][2], const Unit& u, int wr, int wc, int fr, int fq, const float (&rsv)[8]) const {
;     ...
;             for (int m = 0; m < 4; ++m) { const int row = row0 + ai * HALF + m * 16; bf16_t* rowp = O + (size_t)row * 3072 + col0; const float scr_ = sc * rsv[ai * 4 + m];
;                 f32x4 c0 = {1.f, 1.f, 1.f, 1.f}, c1 = c0, s0 = {0.f, 0.f, 0.f, 0.f}, s1 = s0;
;                 if (rotw) { const f32x4* rp = (const f32x4*)(rot + (size_t)row * 16); c0 = rp[0]; c1 = rp[1]; s0 = rp[2]; s1 = rp[3]; }
; #pragma unroll
;                 for (int bj = 0; bj < 2; ++bj) { f32x4 v0 = acc[ai][bj][m][0], v1 = acc[ai][bj][m][1];
;                     if (rotw) { f32x4 p0, p1;
; #pragma unroll
;                         for (int j = 0; j < 4; ++j) { const float a0 = v0[j], a1 = v1[j]; p0[j] = __int_as_float(__builtin_amdgcn_ds_bpermute(pidx, __float_as_int(a0))); p1[j] = __int_as_float(__builtin_amdgcn_ds_bpermute(pidx, __float_as_int(a1))); }
;                         if (rotl) { v0 = v0 * c0 + (p0 * s0) * sgn; v1 = v1 * c1 + (p1 * s1) * sgn; } }
;                     v0 = v0 * scr_; v1 = v1 * scr_; u32x4 w; w.x = cvt_pk_bf16(v0[0], v0[1]); w.y = cvt_pk_bf16(v0[2], v0[3]); w.z = cvt_pk_bf16(v1[0], v1[1]); w.w = cvt_pk_bf16(v1[2], v1[3]);
;                     *(u32x4*)(rowp + bj * HALF) = w; } }
.LBB0_121:
	s_waitcnt lgkmcnt(0)
	v_mov_b64_e32 v[118:119], s[14:15]
	v_mul_f32_e32 v116, v161, v180
	v_mad_i64_i32 v[114:115], s[42:43], v114, s97, v[118:119]
	v_lshl_add_u64 v[114:115], v[162:163], 1, v[114:115]
	v_pk_mul_f32 v[118:119], v[116:117], v[92:93] op_sel_hi:[0,1]
	v_pk_mul_f32 v[92:93], v[116:117], v[90:91] op_sel_hi:[0,1]
	s_and_b64 vcc, exec, s[6:7]
	v_pk_mul_f32 v[96:97], v[116:117], v[96:97] op_sel_hi:[0,1]
	v_pk_mul_f32 v[94:95], v[116:117], v[94:95] op_sel_hi:[0,1]
	v_cvt_pk_bf16_f32 v90, v94, v95
	v_cvt_pk_bf16_f32 v91, v96, v97
	v_cvt_pk_bf16_f32 v92, v92, v93
	v_cvt_pk_bf16_f32 v93, v118, v119
	v_subrev_u32_e32 v239, s14, v114
	global_store_dwordx4 v239, v[90:93], s[14:15] sc1
	s_cbranch_vccnz .LBB0_125
	ds_bpermute_b32 v94, v173, v86
	ds_bpermute_b32 v90, v173, v82
	ds_bpermute_b32 v95, v173, v87
	ds_bpermute_b32 v91, v173, v83
	ds_bpermute_b32 v96, v173, v88
	ds_bpermute_b32 v92, v173, v84
	ds_bpermute_b32 v97, v173, v89
	ds_bpermute_b32 v93, v173, v85
	s_and_saveexec_b64 s[76:77], s[8:9]
	s_cbranch_execz .LBB0_124
	s_waitcnt vmcnt(2) lgkmcnt(1)
	v_pk_mul_f32 v[96:97], v[112:113], v[96:97]
	v_pk_mul_f32 v[94:95], v[110:111], v[94:95]
	s_waitcnt vmcnt(1) lgkmcnt(0)
	v_pk_mul_f32 v[92:93], v[108:109], v[92:93]
	v_pk_mul_f32 v[90:91], v[106:107], v[90:91]
	v_pk_mul_f32 v[96:97], v[154:155], v[96:97]
	v_pk_mul_f32 v[94:95], v[152:153], v[94:95]
	v_pk_mul_f32 v[92:93], v[154:155], v[92:93]
	v_pk_mul_f32 v[90:91], v[152:153], v[90:91]
	v_pk_fma_f32 v[88:89], v[88:89], v[104:105], v[96:97]
	v_pk_fma_f32 v[86:87], v[86:87], v[102:103], v[94:95]
	v_pk_fma_f32 v[84:85], v[84:85], v[100:101], v[92:93]
	v_pk_fma_f32 v[82:83], v[82:83], v[98:99], v[90:91]

; __device__ __forceinline__ unsigned cvt_pk_bf16(float lo, float hi) { unsigned r; asm volatile("v_cvt_pk_bf16_f32 %0, %1, %2" : "=v"(r) : "v"(lo), "v"(hi)); return r; }
;     __device__ __forceinline__ void operator()(const f32x4 (&acc)[2][2][4][2], const Unit& u, int wr, int wc, int fr, int fq, const float (&rsv)[8]) const {
;     ...
;             for (int m = 0; m < 4; ++m) { const int row = row0 + ai * HALF + m * 16; bf16_t* rowp = O + (size_t)row * 3072 + col0; const float scr_ = sc * rsv[ai * 4 + m];
;                 f32x4 c0 = {1.f, 1.f, 1.f, 1.f}, c1 = c0, s0 = {0.f, 0.f, 0.f, 0.f}, s1 = s0;
;                 if (rotw) { const f32x4* rp = (const f32x4*)(rot + (size_t)row * 16); c0 = rp[0]; c1 = rp[1]; s0 = rp[2]; s1 = rp[3]; }
; #pragma unroll
;                 for (int bj = 0; bj < 2; ++bj) { f32x4 v0 = acc[ai][bj][m][0], v1 = acc[ai][bj][m][1];
;                     if (rotw) { f32x4 p0, p1;
; #pragma unroll
;                         for (int j = 0; j < 4; ++j) { const float a0 = v0[j], a1 = v1[j]; p0[j] = __int_as_float(__builtin_amdgcn_ds_bpermute(pidx, __float_as_int(a0))); p1[j] = __int_as_float(__builtin_amdgcn_ds_bpermute(pidx, __float_as_int(a1))); }
;                         if (rotl) { v0 = v0 * c0 + (p0 * s0) * sgn; v1 = v1 * c1 + (p1 * s1) * sgn; } }
;                     v0 = v0 * scr_; v1 = v1 * scr_; u32x4 w; w.x = cvt_pk_bf16(v0[0], v0[1]); w.y = cvt_pk_bf16(v0[2], v0[3]); w.z = cvt_pk_bf16(v1[0], v1[1]); w.w = cvt_pk_bf16(v1[2], v1[3]);
;                     *(u32x4*)(rowp + bj * HALF) = w; } }
.LBB0_125:
	v_mov_b32_e32 v117, v116
	s_waitcnt lgkmcnt(6)
	v_mov_b32_e32 v90, v116
	s_waitcnt lgkmcnt(4)
	v_mov_b32_e32 v91, v116
	s_waitcnt vmcnt(3)
	v_or_b32_e32 v98, 48, v160
	v_pk_mul_f32 v[88:89], v[90:91], v[88:89]
	v_pk_mul_f32 v[90:91], v[90:91], v[84:85]
	v_pk_mul_f32 v[84:85], v[116:117], v[82:83]
	s_and_b64 vcc, exec, s[6:7]
	v_ashrrev_i32_e32 v99, 31, v98
	v_pk_mul_f32 v[86:87], v[116:117], v[86:87]
	s_nop 0
	v_cvt_pk_bf16_f32 v82, v86, v87
	v_cvt_pk_bf16_f32 v83, v88, v89
	v_cvt_pk_bf16_f32 v84, v84, v85
	v_cvt_pk_bf16_f32 v85, v90, v91
	v_subrev_u32_e32 v239, s14, v114
	global_store_dwordx4 v239, v[82:85], s[14:15] offset:256 sc1
	s_cbranch_vccnz .LBB0_127
	s_nop 0
	v_lshlrev_b64 v[82:83], 6, v[98:99]
	v_lshl_add_u64 v[90:91], s[16:17], 0, v[82:83]
	global_load_dwordx4 v[86:89], v[90:91], off
	global_load_dwordx4 v[82:85], v[90:91], off offset:16
	s_waitcnt lgkmcnt(1)
	global_load_dwordx4 v[94:97], v[90:91], off offset:32
	s_waitcnt lgkmcnt(0)
	global_load_dwordx4 v[90:93], v[90:91], off offset:48
	s_and_b64 vcc, exec, s[6:7]
	s_cbranch_vccz .LBB0_128
	s_branch .LBB0_131

; __device__ __forceinline__ unsigned cvt_pk_bf16(float lo, float hi) { unsigned r; asm volatile("v_cvt_pk_bf16_f32 %0, %1, %2" : "=v"(r) : "v"(lo), "v"(hi)); return r; }
;     __device__ __forceinline__ void operator()(const f32x4 (&acc)[2][2][4][2], const Unit& u, int wr, int wc, int fr, int fq, const float (&rsv)[8]) const {
;     ...
;             for (int m = 0; m < 4; ++m) { const int row = row0 + ai * HALF + m * 16; bf16_t* rowp = O + (size_t)row * 3072 + col0; const float scr_ = sc * rsv[ai * 4 + m];
;                 f32x4 c0 = {1.f, 1.f, 1.f, 1.f}, c1 = c0, s0 = {0.f, 0.f, 0.f, 0.f}, s1 = s0;
;                 if (rotw) { const f32x4* rp = (const f32x4*)(rot + (size_t)row * 16); c0 = rp[0]; c1 = rp[1]; s0 = rp[2]; s1 = rp[3]; }
; #pragma unroll
;                 for (int bj = 0; bj < 2; ++bj) { f32x4 v0 = acc[ai][bj][m][0], v1 = acc[ai][bj][m][1];
;                     if (rotw) { f32x4 p0, p1;
; #pragma unroll
;                         for (int j = 0; j < 4; ++j) { const float a0 = v0[j], a1 = v1[j]; p0[j] = __int_as_float(__builtin_amdgcn_ds_bpermute(pidx, __float_as_int(a0))); p1[j] = __int_as_float(__builtin_amdgcn_ds_bpermute(pidx, __float_as_int(a1))); }
;                         if (rotl) { v0 = v0 * c0 + (p0 * s0) * sgn; v1 = v1 * c1 + (p1 * s1) * sgn; } }
;                     v0 = v0 * scr_; v1 = v1 * scr_; u32x4 w; w.x = cvt_pk_bf16(v0[0], v0[1]); w.y = cvt_pk_bf16(v0[2], v0[3]); w.z = cvt_pk_bf16(v1[0], v1[1]); w.w = cvt_pk_bf16(v1[2], v1[3]);
;                     *(u32x4*)(rowp + bj * HALF) = w; } }
.LBB0_131:
	s_waitcnt lgkmcnt(0)
	v_mov_b64_e32 v[102:103], s[14:15]
	v_mul_f32_e32 v100, v161, v179
	v_mad_i64_i32 v[98:99], s[42:43], v98, s97, v[102:103]
	v_lshl_add_u64 v[98:99], v[162:163], 1, v[98:99]
	v_pk_mul_f32 v[102:103], v[100:101], v[76:77] op_sel_hi:[0,1]
	v_pk_mul_f32 v[76:77], v[100:101], v[74:75] op_sel_hi:[0,1]
	s_and_b64 vcc, exec, s[6:7]
	v_pk_mul_f32 v[80:81], v[100:101], v[80:81] op_sel_hi:[0,1]
	v_pk_mul_f32 v[78:79], v[100:101], v[78:79] op_sel_hi:[0,1]
	v_cvt_pk_bf16_f32 v74, v78, v79
	v_cvt_pk_bf16_f32 v75, v80, v81
	v_cvt_pk_bf16_f32 v76, v76, v77
	v_cvt_pk_bf16_f32 v77, v102, v103
	v_subrev_u32_e32 v239, s14, v98
	global_store_dwordx4 v239, v[74:77], s[14:15] sc1
	s_cbranch_vccnz .LBB0_135
	ds_bpermute_b32 v78, v173, v70
	ds_bpermute_b32 v74, v173, v66
	ds_bpermute_b32 v79, v173, v71
	ds_bpermute_b32 v75, v173, v67
	ds_bpermute_b32 v80, v173, v72
	ds_bpermute_b32 v76, v173, v68
	ds_bpermute_b32 v81, v173, v73
	ds_bpermute_b32 v77, v173, v69
	s_and_saveexec_b64 s[76:77], s[8:9]
	s_cbranch_execz .LBB0_134
	s_waitcnt vmcnt(2) lgkmcnt(1)
	v_pk_mul_f32 v[80:81], v[96:97], v[80:81]
	v_pk_mul_f32 v[78:79], v[94:95], v[78:79]
	s_waitcnt vmcnt(1) lgkmcnt(0)
	v_pk_mul_f32 v[76:77], v[92:93], v[76:77]
	v_pk_mul_f32 v[74:75], v[90:91], v[74:75]
	v_pk_mul_f32 v[80:81], v[154:155], v[80:81]
	v_pk_mul_f32 v[78:79], v[152:153], v[78:79]
	v_pk_mul_f32 v[76:77], v[154:155], v[76:77]
	v_pk_mul_f32 v[74:75], v[152:153], v[74:75]
	v_pk_fma_f32 v[72:73], v[72:73], v[88:89], v[80:81]
	v_pk_fma_f32 v[70:71], v[70:71], v[86:87], v[78:79]
	v_pk_fma_f32 v[68:69], v[68:69], v[84:85], v[76:77]
	v_pk_fma_f32 v[66:67], v[66:67], v[82:83], v[74:75]

; __device__ __forceinline__ unsigned cvt_pk_bf16(float lo, float hi) { unsigned r; asm volatile("v_cvt_pk_bf16_f32 %0, %1, %2" : "=v"(r) : "v"(lo), "v"(hi)); return r; }
;     __device__ __forceinline__ void operator()(const f32x4 (&acc)[2][2][4][2], const Unit& u, int wr, int wc, int fr, int fq, const float (&rsv)[8]) const {
;     ...
;             for (int m = 0; m < 4; ++m) { const int row = row0 + ai * HALF + m * 16; bf16_t* rowp = O + (size_t)row * 3072 + col0; const float scr_ = sc * rsv[ai * 4 + m];
;                 f32x4 c0 = {1.f, 1.f, 1.f, 1.f}, c1 = c0, s0 = {0.f, 0.f, 0.f, 0.f}, s1 = s0;
;                 if (rotw) { const f32x4* rp = (const f32x4*)(rot + (size_t)row * 16); c0 = rp[0]; c1 = rp[1]; s0 = rp[2]; s1 = rp[3]; }
; #pragma unroll
;                 for (int bj = 0; bj < 2; ++bj) { f32x4 v0 = acc[ai][bj][m][0], v1 = acc[ai][bj][m][1];
;                     if (rotw) { f32x4 p0, p1;
; #pragma unroll
;                         for (int j = 0; j < 4; ++j) { const float a0 = v0[j], a1 = v1[j]; p0[j] = __int_as_float(__builtin_amdgcn_ds_bpermute(pidx, __float_as_int(a0))); p1[j] = __int_as_float(__builtin_amdgcn_ds_bpermute(pidx, __float_as_int(a1))); }
;                         if (rotl) { v0 = v0 * c0 + (p0 * s0) * sgn; v1 = v1 * c1 + (p1 * s1) * sgn; } }
;                     v0 = v0 * scr_; v1 = v1 * scr_; u32x4 w; w.x = cvt_pk_bf16(v0[0], v0[1]); w.y = cvt_pk_bf16(v0[2], v0[3]); w.z = cvt_pk_bf16(v1[0], v1[1]); w.w = cvt_pk_bf16(v1[2], v1[3]);
;                     *(u32x4*)(rowp + bj * HALF) = w; } }
.LBB0_135:
	v_mov_b32_e32 v101, v100
	s_waitcnt vmcnt(3)
	v_add_u32_e32 v82, 0x80, v160
	s_waitcnt lgkmcnt(6)
	v_mov_b32_e32 v74, v100
	s_waitcnt lgkmcnt(4)
	v_mov_b32_e32 v75, v100
	v_ashrrev_i32_e32 v83, 31, v82
	v_pk_mul_f32 v[72:73], v[74:75], v[72:73]
	v_pk_mul_f32 v[74:75], v[74:75], v[68:69]
	v_pk_mul_f32 v[68:69], v[100:101], v[66:67]
	s_and_b64 vcc, exec, s[6:7]
	v_pk_mul_f32 v[70:71], v[100:101], v[70:71]
	s_nop 0
	v_cvt_pk_bf16_f32 v66, v70, v71
	v_cvt_pk_bf16_f32 v67, v72, v73
	v_cvt_pk_bf16_f32 v68, v68, v69
	v_cvt_pk_bf16_f32 v69, v74, v75
	v_subrev_u32_e32 v239, s14, v98
	global_store_dwordx4 v239, v[66:69], s[14:15] offset:256 sc1
	s_cbranch_vccnz .LBB0_137
	s_nop 0
	v_lshlrev_b64 v[66:67], 6, v[82:83]
	v_lshl_add_u64 v[74:75], s[16:17], 0, v[66:67]
	global_load_dwordx4 v[70:73], v[74:75], off
	global_load_dwordx4 v[66:69], v[74:75], off offset:16
	s_waitcnt lgkmcnt(1)
	global_load_dwordx4 v[78:81], v[74:75], off offset:32
	s_waitcnt lgkmcnt(0)
	global_load_dwordx4 v[74:77], v[74:75], off offset:48
	s_and_b64 vcc, exec, s[6:7]
	s_cbranch_vccz .LBB0_138
	s_branch .LBB0_141

; __device__ __forceinline__ unsigned cvt_pk_bf16(float lo, float hi) { unsigned r; asm volatile("v_cvt_pk_bf16_f32 %0, %1, %2" : "=v"(r) : "v"(lo), "v"(hi)); return r; }
;     __device__ __forceinline__ void operator()(const f32x4 (&acc)[2][2][4][2], const Unit& u, int wr, int wc, int fr, int fq, const float (&rsv)[8]) const {
;     ...
;             for (int m = 0; m < 4; ++m) { const int row = row0 + ai * HALF + m * 16; bf16_t* rowp = O + (size_t)row * 3072 + col0; const float scr_ = sc * rsv[ai * 4 + m];
;                 f32x4 c0 = {1.f, 1.f, 1.f, 1.f}, c1 = c0, s0 = {0.f, 0.f, 0.f, 0.f}, s1 = s0;
;                 if (rotw) { const f32x4* rp = (const f32x4*)(rot + (size_t)row * 16); c0 = rp[0]; c1 = rp[1]; s0 = rp[2]; s1 = rp[3]; }
; #pragma unroll
;                 for (int bj = 0; bj < 2; ++bj) { f32x4 v0 = acc[ai][bj][m][0], v1 = acc[ai][bj][m][1];
;                     if (rotw) { f32x4 p0, p1;
; #pragma unroll
;                         for (int j = 0; j < 4; ++j) { const float a0 = v0[j], a1 = v1[j]; p0[j] = __int_as_float(__builtin_amdgcn_ds_bpermute(pidx, __float_as_int(a0))); p1[j] = __int_as_float(__builtin_amdgcn_ds_bpermute(pidx, __float_as_int(a1))); }
;                         if (rotl) { v0 = v0 * c0 + (p0 * s0) * sgn; v1 = v1 * c1 + (p1 * s1) * sgn; } }
;                     v0 = v0 * scr_; v1 = v1 * scr_; u32x4 w; w.x = cvt_pk_bf16(v0[0], v0[1]); w.y = cvt_pk_bf16(v0[2], v0[3]); w.z = cvt_pk_bf16(v1[0], v1[1]); w.w = cvt_pk_bf16(v1[2], v1[3]);
;                     *(u32x4*)(rowp + bj * HALF) = w; } }
.LBB0_141:
	s_waitcnt lgkmcnt(0)
	v_mov_b64_e32 v[86:87], s[14:15]
	v_mul_f32_e32 v84, v161, v178
	v_mad_i64_i32 v[82:83], s[42:43], v82, s97, v[86:87]
	v_lshl_add_u64 v[82:83], v[162:163], 1, v[82:83]
	v_pk_mul_f32 v[86:87], v[84:85], v[60:61] op_sel_hi:[0,1]
	v_pk_mul_f32 v[60:61], v[84:85], v[58:59] op_sel_hi:[0,1]
	s_and_b64 vcc, exec, s[6:7]
	v_pk_mul_f32 v[64:65], v[84:85], v[64:65] op_sel_hi:[0,1]
	v_pk_mul_f32 v[62:63], v[84:85], v[62:63] op_sel_hi:[0,1]
	v_cvt_pk_bf16_f32 v58, v62, v63
	v_cvt_pk_bf16_f32 v59, v64, v65
	v_cvt_pk_bf16_f32 v60, v60, v61
	v_cvt_pk_bf16_f32 v61, v86, v87
	v_subrev_u32_e32 v239, s14, v82
	global_store_dwordx4 v239, v[58:61], s[14:15] sc1
	s_cbranch_vccnz .LBB0_145
	ds_bpermute_b32 v62, v173, v54
	ds_bpermute_b32 v58, v173, v50
	ds_bpermute_b32 v63, v173, v55
	ds_bpermute_b32 v59, v173, v51
	ds_bpermute_b32 v64, v173, v56
	ds_bpermute_b32 v60, v173, v52
	ds_bpermute_b32 v65, v173, v57
	ds_bpermute_b32 v61, v173, v53
	s_and_saveexec_b64 s[76:77], s[8:9]
	s_cbranch_execz .LBB0_144
	s_waitcnt vmcnt(2) lgkmcnt(1)
	v_pk_mul_f32 v[64:65], v[80:81], v[64:65]
	v_pk_mul_f32 v[62:63], v[78:79], v[62:63]
	s_waitcnt vmcnt(1) lgkmcnt(0)
	v_pk_mul_f32 v[60:61], v[76:77], v[60:61]
	v_pk_mul_f32 v[58:59], v[74:75], v[58:59]
	v_pk_mul_f32 v[64:65], v[154:155], v[64:65]
	v_pk_mul_f32 v[62:63], v[152:153], v[62:63]
	v_pk_mul_f32 v[60:61], v[154:155], v[60:61]
	v_pk_mul_f32 v[58:59], v[152:153], v[58:59]
	v_pk_fma_f32 v[56:57], v[56:57], v[72:73], v[64:65]
	v_pk_fma_f32 v[54:55], v[54:55], v[70:71], v[62:63]
	v_pk_fma_f32 v[52:53], v[52:53], v[68:69], v[60:61]
	v_pk_fma_f32 v[50:51], v[50:51], v[66:67], v[58:59]

; __device__ __forceinline__ unsigned cvt_pk_bf16(float lo, float hi) { unsigned r; asm volatile("v_cvt_pk_bf16_f32 %0, %1, %2" : "=v"(r) : "v"(lo), "v"(hi)); return r; }
;     __device__ __forceinline__ void operator()(const f32x4 (&acc)[2][2][4][2], const Unit& u, int wr, int wc, int fr, int fq, const float (&rsv)[8]) const {
;     ...
;             for (int m = 0; m < 4; ++m) { const int row = row0 + ai * HALF + m * 16; bf16_t* rowp = O + (size_t)row * 3072 + col0; const float scr_ = sc * rsv[ai * 4 + m];
;                 f32x4 c0 = {1.f, 1.f, 1.f, 1.f}, c1 = c0, s0 = {0.f, 0.f, 0.f, 0.f}, s1 = s0;
;                 if (rotw) { const f32x4* rp = (const f32x4*)(rot + (size_t)row * 16); c0 = rp[0]; c1 = rp[1]; s0 = rp[2]; s1 = rp[3]; }
; #pragma unroll
;                 for (int bj = 0; bj < 2; ++bj) { f32x4 v0 = acc[ai][bj][m][0], v1 = acc[ai][bj][m][1];
;                     if (rotw) { f32x4 p0, p1;
; #pragma unroll
;                         for (int j = 0; j < 4; ++j) { const float a0 = v0[j], a1 = v1[j]; p0[j] = __int_as_float(__builtin_amdgcn_ds_bpermute(pidx, __float_as_int(a0))); p1[j] = __int_as_float(__builtin_amdgcn_ds_bpermute(pidx, __float_as_int(a1))); }
;                         if (rotl) { v0 = v0 * c0 + (p0 * s0) * sgn; v1 = v1 * c1 + (p1 * s1) * sgn; } }
;                     v0 = v0 * scr_; v1 = v1 * scr_; u32x4 w; w.x = cvt_pk_bf16(v0[0], v0[1]); w.y = cvt_pk_bf16(v0[2], v0[3]); w.z = cvt_pk_bf16(v1[0], v1[1]); w.w = cvt_pk_bf16(v1[2], v1[3]);
;                     *(u32x4*)(rowp + bj * HALF) = w; } }
.LBB0_145:
	v_mov_b32_e32 v85, v84
	s_waitcnt lgkmcnt(6)
	v_mov_b32_e32 v58, v84
	s_waitcnt lgkmcnt(4)
	v_mov_b32_e32 v59, v84
	s_waitcnt vmcnt(3)
	v_add_u32_e32 v66, 0x90, v160
	v_pk_mul_f32 v[56:57], v[58:59], v[56:57]
	v_pk_mul_f32 v[58:59], v[58:59], v[52:53]
	v_pk_mul_f32 v[52:53], v[84:85], v[50:51]
	s_and_b64 vcc, exec, s[6:7]
	v_ashrrev_i32_e32 v67, 31, v66
	v_pk_mul_f32 v[54:55], v[84:85], v[54:55]
	s_nop 0
	v_cvt_pk_bf16_f32 v50, v54, v55
	v_cvt_pk_bf16_f32 v51, v56, v57
	v_cvt_pk_bf16_f32 v52, v52, v53
	v_cvt_pk_bf16_f32 v53, v58, v59
	v_subrev_u32_e32 v239, s14, v82
	global_store_dwordx4 v239, v[50:53], s[14:15] offset:256 sc1
	s_cbranch_vccnz .LBB0_147
	s_nop 0
	v_lshlrev_b64 v[50:51], 6, v[66:67]
	v_lshl_add_u64 v[58:59], s[16:17], 0, v[50:51]
	global_load_dwordx4 v[54:57], v[58:59], off
	global_load_dwordx4 v[50:53], v[58:59], off offset:16
	s_waitcnt lgkmcnt(1)
	global_load_dwordx4 v[62:65], v[58:59], off offset:32
	s_waitcnt lgkmcnt(0)
	global_load_dwordx4 v[58:61], v[58:59], off offset:48
	s_and_b64 vcc, exec, s[6:7]
	s_cbranch_vccz .LBB0_148
	s_branch .LBB0_151

; __device__ __forceinline__ unsigned cvt_pk_bf16(float lo, float hi) { unsigned r; asm volatile("v_cvt_pk_bf16_f32 %0, %1, %2" : "=v"(r) : "v"(lo), "v"(hi)); return r; }
;     __device__ __forceinline__ void operator()(const f32x4 (&acc)[2][2][4][2], const Unit& u, int wr, int wc, int fr, int fq, const float (&rsv)[8]) const {
;     ...
;             for (int m = 0; m < 4; ++m) { const int row = row0 + ai * HALF + m * 16; bf16_t* rowp = O + (size_t)row * 3072 + col0; const float scr_ = sc * rsv[ai * 4 + m];
;                 f32x4 c0 = {1.f, 1.f, 1.f, 1.f}, c1 = c0, s0 = {0.f, 0.f, 0.f, 0.f}, s1 = s0;
;                 if (rotw) { const f32x4* rp = (const f32x4*)(rot + (size_t)row * 16); c0 = rp[0]; c1 = rp[1]; s0 = rp[2]; s1 = rp[3]; }
; #pragma unroll
;                 for (int bj = 0; bj < 2; ++bj) { f32x4 v0 = acc[ai][bj][m][0], v1 = acc[ai][bj][m][1];
;                     if (rotw) { f32x4 p0, p1;
; #pragma unroll
;                         for (int j = 0; j < 4; ++j) { const float a0 = v0[j], a1 = v1[j]; p0[j] = __int_as_float(__builtin_amdgcn_ds_bpermute(pidx, __float_as_int(a0))); p1[j] = __int_as_float(__builtin_amdgcn_ds_bpermute(pidx, __float_as_int(a1))); }
;                         if (rotl) { v0 = v0 * c0 + (p0 * s0) * sgn; v1 = v1 * c1 + (p1 * s1) * sgn; } }
;                     v0 = v0 * scr_; v1 = v1 * scr_; u32x4 w; w.x = cvt_pk_bf16(v0[0], v0[1]); w.y = cvt_pk_bf16(v0[2], v0[3]); w.z = cvt_pk_bf16(v1[0], v1[1]); w.w = cvt_pk_bf16(v1[2], v1[3]);
;                     *(u32x4*)(rowp + bj * HALF) = w; } }
.LBB0_151:
	s_waitcnt lgkmcnt(0)
	v_mov_b64_e32 v[70:71], s[14:15]
	v_mul_f32_e32 v68, v161, v177
	v_mad_i64_i32 v[66:67], s[42:43], v66, s97, v[70:71]
	v_lshl_add_u64 v[66:67], v[162:163], 1, v[66:67]
	v_pk_mul_f32 v[70:71], v[68:69], v[44:45] op_sel_hi:[0,1]
	v_pk_mul_f32 v[44:45], v[68:69], v[42:43] op_sel_hi:[0,1]
	s_and_b64 vcc, exec, s[6:7]
	v_pk_mul_f32 v[48:49], v[68:69], v[48:49] op_sel_hi:[0,1]
	v_pk_mul_f32 v[46:47], v[68:69], v[46:47] op_sel_hi:[0,1]
	v_cvt_pk_bf16_f32 v42, v46, v47
	v_cvt_pk_bf16_f32 v43, v48, v49
	v_cvt_pk_bf16_f32 v44, v44, v45
	v_cvt_pk_bf16_f32 v45, v70, v71
	v_subrev_u32_e32 v239, s14, v66
	global_store_dwordx4 v239, v[42:45], s[14:15] sc1
	s_cbranch_vccnz .LBB0_155
	ds_bpermute_b32 v46, v173, v38
	ds_bpermute_b32 v42, v173, v34
	ds_bpermute_b32 v47, v173, v39
	ds_bpermute_b32 v43, v173, v35
	ds_bpermute_b32 v48, v173, v40
	ds_bpermute_b32 v44, v173, v36
	ds_bpermute_b32 v49, v173, v41
	ds_bpermute_b32 v45, v173, v37
	s_and_saveexec_b64 s[76:77], s[8:9]
	s_cbranch_execz .LBB0_154
	s_waitcnt vmcnt(2) lgkmcnt(1)
	v_pk_mul_f32 v[48:49], v[64:65], v[48:49]
	v_pk_mul_f32 v[46:47], v[62:63], v[46:47]
	s_waitcnt vmcnt(1) lgkmcnt(0)
	v_pk_mul_f32 v[44:45], v[60:61], v[44:45]
	v_pk_mul_f32 v[42:43], v[58:59], v[42:43]
	v_pk_mul_f32 v[48:49], v[154:155], v[48:49]
	v_pk_mul_f32 v[46:47], v[152:153], v[46:47]
	v_pk_mul_f32 v[44:45], v[154:155], v[44:45]
	v_pk_mul_f32 v[42:43], v[152:153], v[42:43]
	v_pk_fma_f32 v[40:41], v[40:41], v[56:57], v[48:49]
	v_pk_fma_f32 v[38:39], v[38:39], v[54:55], v[46:47]
	v_pk_fma_f32 v[36:37], v[36:37], v[52:53], v[44:45]
	v_pk_fma_f32 v[34:35], v[34:35], v[50:51], v[42:43]

; __device__ __forceinline__ unsigned cvt_pk_bf16(float lo, float hi) { unsigned r; asm volatile("v_cvt_pk_bf16_f32 %0, %1, %2" : "=v"(r) : "v"(lo), "v"(hi)); return r; }
;     __device__ __forceinline__ void operator()(const f32x4 (&acc)[2][2][4][2], const Unit& u, int wr, int wc, int fr, int fq, const float (&rsv)[8]) const {
;     ...
;             for (int m = 0; m < 4; ++m) { const int row = row0 + ai * HALF + m * 16; bf16_t* rowp = O + (size_t)row * 3072 + col0; const float scr_ = sc * rsv[ai * 4 + m];
;                 f32x4 c0 = {1.f, 1.f, 1.f, 1.f}, c1 = c0, s0 = {0.f, 0.f, 0.f, 0.f}, s1 = s0;
;                 if (rotw) { const f32x4* rp = (const f32x4*)(rot + (size_t)row * 16); c0 = rp[0]; c1 = rp[1]; s0 = rp[2]; s1 = rp[3]; }
; #pragma unroll
;                 for (int bj = 0; bj < 2; ++bj) { f32x4 v0 = acc[ai][bj][m][0], v1 = acc[ai][bj][m][1];
;                     if (rotw) { f32x4 p0, p1;
; #pragma unroll
;                         for (int j = 0; j < 4; ++j) { const float a0 = v0[j], a1 = v1[j]; p0[j] = __int_as_float(__builtin_amdgcn_ds_bpermute(pidx, __float_as_int(a0))); p1[j] = __int_as_float(__builtin_amdgcn_ds_bpermute(pidx, __float_as_int(a1))); }
;                         if (rotl) { v0 = v0 * c0 + (p0 * s0) * sgn; v1 = v1 * c1 + (p1 * s1) * sgn; } }
;                     v0 = v0 * scr_; v1 = v1 * scr_; u32x4 w; w.x = cvt_pk_bf16(v0[0], v0[1]); w.y = cvt_pk_bf16(v0[2], v0[3]); w.z = cvt_pk_bf16(v1[0], v1[1]); w.w = cvt_pk_bf16(v1[2], v1[3]);
;                     *(u32x4*)(rowp + bj * HALF) = w; } }
.LBB0_155:
	v_mov_b32_e32 v69, v68
	s_waitcnt lgkmcnt(6)
	v_mov_b32_e32 v42, v68
	s_waitcnt lgkmcnt(4)
	v_mov_b32_e32 v43, v68
	s_waitcnt vmcnt(3)
	v_add_u32_e32 v50, 0xa0, v160
	v_pk_mul_f32 v[40:41], v[42:43], v[40:41]
	v_pk_mul_f32 v[42:43], v[42:43], v[36:37]
	v_pk_mul_f32 v[36:37], v[68:69], v[34:35]
	s_and_b64 vcc, exec, s[6:7]
	v_ashrrev_i32_e32 v51, 31, v50
	v_pk_mul_f32 v[38:39], v[68:69], v[38:39]
	s_nop 0
	v_cvt_pk_bf16_f32 v34, v38, v39
	v_cvt_pk_bf16_f32 v35, v40, v41
	v_cvt_pk_bf16_f32 v36, v36, v37
	v_cvt_pk_bf16_f32 v37, v42, v43
	v_subrev_u32_e32 v239, s14, v66
	global_store_dwordx4 v239, v[34:37], s[14:15] offset:256 sc1
	s_cbranch_vccnz .LBB0_157
	s_nop 0
	v_lshlrev_b64 v[34:35], 6, v[50:51]
	v_lshl_add_u64 v[42:43], s[16:17], 0, v[34:35]
	global_load_dwordx4 v[38:41], v[42:43], off
	global_load_dwordx4 v[34:37], v[42:43], off offset:16
	s_waitcnt lgkmcnt(1)
	global_load_dwordx4 v[46:49], v[42:43], off offset:32
	s_waitcnt lgkmcnt(0)
	global_load_dwordx4 v[42:45], v[42:43], off offset:48
	s_and_b64 vcc, exec, s[6:7]
	s_cbranch_vccz .LBB0_158
	s_branch .LBB0_161

; __device__ __forceinline__ unsigned cvt_pk_bf16(float lo, float hi) { unsigned r; asm volatile("v_cvt_pk_bf16_f32 %0, %1, %2" : "=v"(r) : "v"(lo), "v"(hi)); return r; }
;     __device__ __forceinline__ void operator()(const f32x4 (&acc)[2][2][4][2], const Unit& u, int wr, int wc, int fr, int fq, const float (&rsv)[8]) const {
;     ...
;             for (int m = 0; m < 4; ++m) { const int row = row0 + ai * HALF + m * 16; bf16_t* rowp = O + (size_t)row * 3072 + col0; const float scr_ = sc * rsv[ai * 4 + m];
;                 f32x4 c0 = {1.f, 1.f, 1.f, 1.f}, c1 = c0, s0 = {0.f, 0.f, 0.f, 0.f}, s1 = s0;
;                 if (rotw) { const f32x4* rp = (const f32x4*)(rot + (size_t)row * 16); c0 = rp[0]; c1 = rp[1]; s0 = rp[2]; s1 = rp[3]; }
; #pragma unroll
;                 for (int bj = 0; bj < 2; ++bj) { f32x4 v0 = acc[ai][bj][m][0], v1 = acc[ai][bj][m][1];
;                     if (rotw) { f32x4 p0, p1;
; #pragma unroll
;                         for (int j = 0; j < 4; ++j) { const float a0 = v0[j], a1 = v1[j]; p0[j] = __int_as_float(__builtin_amdgcn_ds_bpermute(pidx, __float_as_int(a0))); p1[j] = __int_as_float(__builtin_amdgcn_ds_bpermute(pidx, __float_as_int(a1))); }
;                         if (rotl) { v0 = v0 * c0 + (p0 * s0) * sgn; v1 = v1 * c1 + (p1 * s1) * sgn; } }
;                     v0 = v0 * scr_; v1 = v1 * scr_; u32x4 w; w.x = cvt_pk_bf16(v0[0], v0[1]); w.y = cvt_pk_bf16(v0[2], v0[3]); w.z = cvt_pk_bf16(v1[0], v1[1]); w.w = cvt_pk_bf16(v1[2], v1[3]);
;                     *(u32x4*)(rowp + bj * HALF) = w; } }
.LBB0_161:
	s_waitcnt lgkmcnt(0)
	v_mov_b64_e32 v[54:55], s[14:15]
	v_mul_f32_e32 v52, v161, v176
	v_mad_i64_i32 v[50:51], s[42:43], v50, s97, v[54:55]
	v_lshl_add_u64 v[50:51], v[162:163], 1, v[50:51]
	v_pk_mul_f32 v[54:55], v[52:53], v[28:29] op_sel_hi:[0,1]
	v_pk_mul_f32 v[28:29], v[52:53], v[26:27] op_sel_hi:[0,1]
	s_and_b64 vcc, exec, s[6:7]
	v_pk_mul_f32 v[32:33], v[52:53], v[32:33] op_sel_hi:[0,1]
	v_pk_mul_f32 v[30:31], v[52:53], v[30:31] op_sel_hi:[0,1]
	v_cvt_pk_bf16_f32 v26, v30, v31
	v_cvt_pk_bf16_f32 v27, v32, v33
	v_cvt_pk_bf16_f32 v28, v28, v29
	v_cvt_pk_bf16_f32 v29, v54, v55
	v_subrev_u32_e32 v239, s14, v50
	global_store_dwordx4 v239, v[26:29], s[14:15] sc1
	s_cbranch_vccnz .LBB0_165
	ds_bpermute_b32 v30, v173, v22
	ds_bpermute_b32 v26, v173, v18
	ds_bpermute_b32 v31, v173, v23
	ds_bpermute_b32 v27, v173, v19
	ds_bpermute_b32 v32, v173, v24
	ds_bpermute_b32 v28, v173, v20
	ds_bpermute_b32 v33, v173, v25
	ds_bpermute_b32 v29, v173, v21
	s_and_saveexec_b64 s[76:77], s[8:9]
	s_cbranch_execz .LBB0_164
	s_waitcnt vmcnt(2) lgkmcnt(1)
	v_pk_mul_f32 v[32:33], v[48:49], v[32:33]
	v_pk_mul_f32 v[30:31], v[46:47], v[30:31]
	s_waitcnt vmcnt(1) lgkmcnt(0)
	v_pk_mul_f32 v[28:29], v[44:45], v[28:29]
	v_pk_mul_f32 v[26:27], v[42:43], v[26:27]
	v_pk_mul_f32 v[32:33], v[154:155], v[32:33]
	v_pk_mul_f32 v[30:31], v[152:153], v[30:31]
	v_pk_mul_f32 v[28:29], v[154:155], v[28:29]
	v_pk_mul_f32 v[26:27], v[152:153], v[26:27]
	v_pk_fma_f32 v[24:25], v[24:25], v[40:41], v[32:33]
	v_pk_fma_f32 v[22:23], v[22:23], v[38:39], v[30:31]
	v_pk_fma_f32 v[20:21], v[20:21], v[36:37], v[28:29]
	v_pk_fma_f32 v[18:19], v[18:19], v[34:35], v[26:27]

; __device__ __forceinline__ unsigned cvt_pk_bf16(float lo, float hi) { unsigned r; asm volatile("v_cvt_pk_bf16_f32 %0, %1, %2" : "=v"(r) : "v"(lo), "v"(hi)); return r; }
;     __device__ __forceinline__ void operator()(const f32x4 (&acc)[2][2][4][2], const Unit& u, int wr, int wc, int fr, int fq, const float (&rsv)[8]) const {
;     ...
;             for (int m = 0; m < 4; ++m) { const int row = row0 + ai * HALF + m * 16; bf16_t* rowp = O + (size_t)row * 3072 + col0; const float scr_ = sc * rsv[ai * 4 + m];
;                 f32x4 c0 = {1.f, 1.f, 1.f, 1.f}, c1 = c0, s0 = {0.f, 0.f, 0.f, 0.f}, s1 = s0;
;                 if (rotw) { const f32x4* rp = (const f32x4*)(rot + (size_t)row * 16); c0 = rp[0]; c1 = rp[1]; s0 = rp[2]; s1 = rp[3]; }
; #pragma unroll
;                 for (int bj = 0; bj < 2; ++bj) { f32x4 v0 = acc[ai][bj][m][0], v1 = acc[ai][bj][m][1];
;                     if (rotw) { f32x4 p0, p1;
; #pragma unroll
;                         for (int j = 0; j < 4; ++j) { const float a0 = v0[j], a1 = v1[j]; p0[j] = __int_as_float(__builtin_amdgcn_ds_bpermute(pidx, __float_as_int(a0))); p1[j] = __int_as_float(__builtin_amdgcn_ds_bpermute(pidx, __float_as_int(a1))); }
;                         if (rotl) { v0 = v0 * c0 + (p0 * s0) * sgn; v1 = v1 * c1 + (p1 * s1) * sgn; } }
;                     v0 = v0 * scr_; v1 = v1 * scr_; u32x4 w; w.x = cvt_pk_bf16(v0[0], v0[1]); w.y = cvt_pk_bf16(v0[2], v0[3]); w.z = cvt_pk_bf16(v1[0], v1[1]); w.w = cvt_pk_bf16(v1[2], v1[3]);
;                     *(u32x4*)(rowp + bj * HALF) = w; } }
.LBB0_165:
	v_mov_b32_e32 v53, v52
	s_waitcnt lgkmcnt(6)
	v_mov_b32_e32 v26, v52
	s_waitcnt lgkmcnt(4)
	v_mov_b32_e32 v27, v52
	s_waitcnt vmcnt(3)
	v_add_u32_e32 v34, 0xb0, v160
	v_pk_mul_f32 v[24:25], v[26:27], v[24:25]
	v_pk_mul_f32 v[26:27], v[26:27], v[20:21]
	v_pk_mul_f32 v[20:21], v[52:53], v[18:19]
	s_and_b64 vcc, exec, s[6:7]
	v_ashrrev_i32_e32 v35, 31, v34
	v_pk_mul_f32 v[22:23], v[52:53], v[22:23]
	s_nop 0
	v_cvt_pk_bf16_f32 v18, v22, v23
	v_cvt_pk_bf16_f32 v19, v24, v25
	v_cvt_pk_bf16_f32 v20, v20, v21
	v_cvt_pk_bf16_f32 v21, v26, v27
	v_subrev_u32_e32 v239, s14, v50
	global_store_dwordx4 v239, v[18:21], s[14:15] offset:256 sc1
	s_cbranch_vccnz .LBB0_167
	s_nop 0
	v_lshlrev_b64 v[18:19], 6, v[34:35]
	v_lshl_add_u64 v[26:27], s[16:17], 0, v[18:19]
	global_load_dwordx4 v[22:25], v[26:27], off
	global_load_dwordx4 v[18:21], v[26:27], off offset:16
	s_waitcnt lgkmcnt(1)
	global_load_dwordx4 v[30:33], v[26:27], off offset:32
	s_waitcnt lgkmcnt(0)
	global_load_dwordx4 v[26:29], v[26:27], off offset:48
	s_and_b64 vcc, exec, s[6:7]
	s_cbranch_vccz .LBB0_168
	s_branch .LBB0_171

; __device__ __forceinline__ unsigned cvt_pk_bf16(float lo, float hi) { unsigned r; asm volatile("v_cvt_pk_bf16_f32 %0, %1, %2" : "=v"(r) : "v"(lo), "v"(hi)); return r; }
;     __device__ __forceinline__ void operator()(const f32x4 (&acc)[2][2][4][2], const Unit& u, int wr, int wc, int fr, int fq, const float (&rsv)[8]) const {
;     ...
;             for (int m = 0; m < 4; ++m) { const int row = row0 + ai * HALF + m * 16; bf16_t* rowp = O + (size_t)row * 3072 + col0; const float scr_ = sc * rsv[ai * 4 + m];
;                 f32x4 c0 = {1.f, 1.f, 1.f, 1.f}, c1 = c0, s0 = {0.f, 0.f, 0.f, 0.f}, s1 = s0;
;                 if (rotw) { const f32x4* rp = (const f32x4*)(rot + (size_t)row * 16); c0 = rp[0]; c1 = rp[1]; s0 = rp[2]; s1 = rp[3]; }
; #pragma unroll
;                 for (int bj = 0; bj < 2; ++bj) { f32x4 v0 = acc[ai][bj][m][0], v1 = acc[ai][bj][m][1];
;                     if (rotw) { f32x4 p0, p1;
; #pragma unroll
;                         for (int j = 0; j < 4; ++j) { const float a0 = v0[j], a1 = v1[j]; p0[j] = __int_as_float(__builtin_amdgcn_ds_bpermute(pidx, __float_as_int(a0))); p1[j] = __int_as_float(__builtin_amdgcn_ds_bpermute(pidx, __float_as_int(a1))); }
;                         if (rotl) { v0 = v0 * c0 + (p0 * s0) * sgn; v1 = v1 * c1 + (p1 * s1) * sgn; } }
;                     v0 = v0 * scr_; v1 = v1 * scr_; u32x4 w; w.x = cvt_pk_bf16(v0[0], v0[1]); w.y = cvt_pk_bf16(v0[2], v0[3]); w.z = cvt_pk_bf16(v1[0], v1[1]); w.w = cvt_pk_bf16(v1[2], v1[3]);
;                     *(u32x4*)(rowp + bj * HALF) = w; } }
.LBB0_171:
	s_waitcnt lgkmcnt(0)
	v_mov_b64_e32 v[38:39], s[14:15]
	v_mul_f32_e32 v36, v161, v175
	v_mad_i64_i32 v[34:35], s[42:43], v34, s97, v[38:39]
	v_lshl_add_u64 v[34:35], v[162:163], 1, v[34:35]
	v_pk_mul_f32 v[38:39], v[36:37], v[12:13] op_sel_hi:[0,1]
	v_pk_mul_f32 v[12:13], v[36:37], v[10:11] op_sel_hi:[0,1]
	s_and_b64 vcc, exec, s[6:7]
	v_pk_mul_f32 v[16:17], v[36:37], v[16:17] op_sel_hi:[0,1]
	v_pk_mul_f32 v[14:15], v[36:37], v[14:15] op_sel_hi:[0,1]
	v_cvt_pk_bf16_f32 v10, v14, v15
	v_cvt_pk_bf16_f32 v11, v16, v17
	v_cvt_pk_bf16_f32 v12, v12, v13
	v_cvt_pk_bf16_f32 v13, v38, v39
	v_subrev_u32_e32 v239, s14, v34
	global_store_dwordx4 v239, v[10:13], s[14:15] sc1
	s_cbranch_vccnz .LBB0_175
	ds_bpermute_b32 v14, v173, v6
	ds_bpermute_b32 v10, v173, v2
	ds_bpermute_b32 v15, v173, v7
	ds_bpermute_b32 v11, v173, v3
	ds_bpermute_b32 v16, v173, v8
	ds_bpermute_b32 v12, v173, v4
	ds_bpermute_b32 v17, v173, v9
	ds_bpermute_b32 v13, v173, v5
	s_and_saveexec_b64 s[6:7], s[8:9]
	s_cbranch_execz .LBB0_174
	s_waitcnt vmcnt(2) lgkmcnt(1)
	v_pk_mul_f32 v[16:17], v[32:33], v[16:17]
	v_pk_mul_f32 v[14:15], v[30:31], v[14:15]
	s_waitcnt vmcnt(1) lgkmcnt(0)
	v_pk_mul_f32 v[12:13], v[28:29], v[12:13]
	v_pk_mul_f32 v[10:11], v[26:27], v[10:11]
	v_pk_mul_f32 v[16:17], v[154:155], v[16:17]
	v_pk_mul_f32 v[14:15], v[152:153], v[14:15]
	v_pk_mul_f32 v[12:13], v[154:155], v[12:13]
	v_pk_mul_f32 v[10:11], v[152:153], v[10:11]
	v_pk_fma_f32 v[8:9], v[8:9], v[24:25], v[16:17]
	v_pk_fma_f32 v[6:7], v[6:7], v[22:23], v[14:15]
	v_pk_fma_f32 v[4:5], v[4:5], v[20:21], v[12:13]
	v_pk_fma_f32 v[2:3], v[2:3], v[18:19], v[10:11]

; __device__ __forceinline__ unsigned cvt_pk_bf16(float lo, float hi) { unsigned r; asm volatile("v_cvt_pk_bf16_f32 %0, %1, %2" : "=v"(r) : "v"(lo), "v"(hi)); return r; }
;     __device__ __forceinline__ void operator()(const f32x4 (&acc)[2][2][4][2], const Unit& u, int wr, int wc, int fr, int fq, const float (&rsv)[8]) const {
;     ...
;             for (int m = 0; m < 4; ++m) { const int row = row0 + ai * HALF + m * 16; bf16_t* rowp = O + (size_t)row * 3072 + col0; const float scr_ = sc * rsv[ai * 4 + m];
;                 f32x4 c0 = {1.f, 1.f, 1.f, 1.f}, c1 = c0, s0 = {0.f, 0.f, 0.f, 0.f}, s1 = s0;
;                 if (rotw) { const f32x4* rp = (const f32x4*)(rot + (size_t)row * 16); c0 = rp[0]; c1 = rp[1]; s0 = rp[2]; s1 = rp[3]; }
; #pragma unroll
;                 for (int bj = 0; bj < 2; ++bj) { f32x4 v0 = acc[ai][bj][m][0], v1 = acc[ai][bj][m][1];
;                     if (rotw) { f32x4 p0, p1;
; #pragma unroll
;                         for (int j = 0; j < 4; ++j) { const float a0 = v0[j], a1 = v1[j]; p0[j] = __int_as_float(__builtin_amdgcn_ds_bpermute(pidx, __float_as_int(a0))); p1[j] = __int_as_float(__builtin_amdgcn_ds_bpermute(pidx, __float_as_int(a1))); }
;                         if (rotl) { v0 = v0 * c0 + (p0 * s0) * sgn; v1 = v1 * c1 + (p1 * s1) * sgn; } }
;                     v0 = v0 * scr_; v1 = v1 * scr_; u32x4 w; w.x = cvt_pk_bf16(v0[0], v0[1]); w.y = cvt_pk_bf16(v0[2], v0[3]); w.z = cvt_pk_bf16(v1[0], v1[1]); w.w = cvt_pk_bf16(v1[2], v1[3]);
;                     *(u32x4*)(rowp + bj * HALF) = w; } }
.LBB0_175:
	v_mov_b32_e32 v37, v36
	s_waitcnt lgkmcnt(6)
	v_mov_b32_e32 v10, v36
	s_waitcnt lgkmcnt(4)
	v_mov_b32_e32 v11, v36
	v_pk_mul_f32 v[8:9], v[10:11], v[8:9]
	v_pk_mul_f32 v[10:11], v[10:11], v[4:5]
	v_pk_mul_f32 v[4:5], v[36:37], v[2:3]
	s_andn2_b64 vcc, exec, s[4:5]
	s_mov_b64 s[4:5], -1
	v_pk_mul_f32 v[6:7], v[36:37], v[6:7]
	s_nop 0
	v_cvt_pk_bf16_f32 v2, v6, v7
	v_cvt_pk_bf16_f32 v3, v8, v9
	v_cvt_pk_bf16_f32 v4, v4, v5
	v_cvt_pk_bf16_f32 v5, v10, v11
	v_subrev_u32_e32 v239, s14, v34
	global_store_dwordx4 v239, v[2:5], s[14:15] offset:256 sc1
	s_cbranch_vccnz .LBB0_88
	s_andn2_b64 vcc, exec, s[12:13]
	s_cbranch_vccnz .LBB0_87
	s_barrier
	s_branch .LBB0_87

; __device__ __forceinline__ unsigned cvt_pk_bf16(float lo, float hi) { unsigned r; asm volatile("v_cvt_pk_bf16_f32 %0, %1, %2" : "=v"(r) : "v"(lo), "v"(hi)); return r; }
;     __device__ __forceinline__ void operator()(const f32x4 (&acc)[2][2][4][2], const Unit& u, int wr, int wc, int fr, int fq, const float (&rsv)[8]) const {
;     ...
;             for (int m = 0; m < 4; ++m) { bf16_t* rowp = O + (size_t)(row0 + ai * HALF + m * 16) * ldc + col0;
; #pragma unroll
;                 for (int bj = 0; bj < 2; ++bj) { const f32x4 v0 = acc[ai][bj][m][0], v1 = acc[ai][bj][m][1];
;                     u32x4 w; w.x = cvt_pk_bf16(v0[0], v0[1]); w.y = cvt_pk_bf16(v0[2], v0[3]); w.z = cvt_pk_bf16(v1[0], v1[1]); w.w = cvt_pk_bf16(v1[2], v1[3]);
;                     *(u32x4*)(rowp + bj * HALF) = w; } }
.LBB0_488:
	v_lshl_add_u32 v146, s16, 8, v142
	v_lshl_or_b32 v140, s38, 8, v144
	v_ashrrev_i32_e32 v147, 31, v146
	v_ashrrev_i32_e32 v141, 31, v140
	v_lshlrev_b64 v[148:149], 11, v[146:147]
	v_lshl_add_u64 v[148:149], s[8:9], 0, v[148:149]
	v_lshlrev_b64 v[150:151], 1, v[140:141]
	v_lshl_add_u64 v[140:141], v[148:149], 0, v[150:151]
	v_cvt_pk_bf16_f32 v126, v126, v127
	v_cvt_pk_bf16_f32 v127, v128, v129
	v_cvt_pk_bf16_f32 v128, v122, v123
	v_cvt_pk_bf16_f32 v129, v124, v125
	v_subrev_u32_e32 v218, s8, v140
	global_store_dwordx4 v218, v[126:129], s[8:9] sc1
	v_cvt_pk_bf16_f32 v114, v114, v115
	v_cvt_pk_bf16_f32 v115, v116, v117
	v_cvt_pk_bf16_f32 v116, v106, v107
	v_or_b32_e32 v106, 16, v146
	v_ashrrev_i32_e32 v107, 31, v106
	v_lshlrev_b64 v[106:107], 11, v[106:107]
	v_lshl_add_u64 v[106:107], s[8:9], 0, v[106:107]
	v_cvt_pk_bf16_f32 v117, v108, v109
	v_subrev_u32_e32 v218, s8, v140
	global_store_dwordx4 v218, v[114:117], s[8:9] offset:256 sc1
	s_nop 1
	v_lshl_add_u64 v[114:115], v[106:107], 0, v[150:151]
	v_cvt_pk_bf16_f32 v106, v118, v119
	v_cvt_pk_bf16_f32 v107, v120, v121
	v_cvt_pk_bf16_f32 v108, v110, v111
	v_cvt_pk_bf16_f32 v109, v112, v113
	v_subrev_u32_e32 v218, s8, v114
	global_store_dwordx4 v218, v[106:109], s[8:9] sc1
	v_cvt_pk_bf16_f32 v98, v98, v99
	v_cvt_pk_bf16_f32 v99, v100, v101
	v_cvt_pk_bf16_f32 v100, v90, v91
	v_or_b32_e32 v90, 32, v146
	v_ashrrev_i32_e32 v91, 31, v90
	v_lshlrev_b64 v[90:91], 11, v[90:91]
	v_lshl_add_u64 v[90:91], s[8:9], 0, v[90:91]
	v_cvt_pk_bf16_f32 v101, v92, v93
	v_subrev_u32_e32 v218, s8, v114
	global_store_dwordx4 v218, v[98:101], s[8:9] offset:256 sc1
	s_nop 1
	v_lshl_add_u64 v[98:99], v[90:91], 0, v[150:151]
	v_cvt_pk_bf16_f32 v90, v102, v103
	v_cvt_pk_bf16_f32 v91, v104, v105
	v_cvt_pk_bf16_f32 v92, v94, v95
	v_cvt_pk_bf16_f32 v93, v96, v97
	v_subrev_u32_e32 v218, s8, v98
	global_store_dwordx4 v218, v[90:93], s[8:9] sc1
	v_cvt_pk_bf16_f32 v82, v82, v83
	v_cvt_pk_bf16_f32 v83, v84, v85
	v_cvt_pk_bf16_f32 v84, v74, v75
	v_or_b32_e32 v74, 48, v146
	v_ashrrev_i32_e32 v75, 31, v74
	v_lshlrev_b64 v[74:75], 11, v[74:75]
	v_lshl_add_u64 v[74:75], s[8:9], 0, v[74:75]
	v_cvt_pk_bf16_f32 v85, v76, v77
	v_subrev_u32_e32 v218, s8, v98
	global_store_dwordx4 v218, v[82:85], s[8:9] offset:256 sc1
	s_nop 1
	v_lshl_add_u64 v[82:83], v[74:75], 0, v[150:151]
	v_cvt_pk_bf16_f32 v74, v86, v87
	v_cvt_pk_bf16_f32 v75, v88, v89
	v_cvt_pk_bf16_f32 v76, v78, v79
	v_cvt_pk_bf16_f32 v77, v80, v81
	v_subrev_u32_e32 v218, s8, v82
	global_store_dwordx4 v218, v[74:77], s[8:9] sc1
	v_cvt_pk_bf16_f32 v70, v70, v71
	v_cvt_pk_bf16_f32 v71, v72, v73
	v_cvt_pk_bf16_f32 v72, v66, v67
	v_cvt_pk_bf16_f32 v73, v68, v69
	v_subrev_u32_e32 v218, s8, v82
	global_store_dwordx4 v218, v[70:73], s[8:9] offset:256 sc1
	v_cvt_pk_bf16_f32 v62, v62, v63
	v_cvt_pk_bf16_f32 v63, v64, v65
	v_cvt_pk_bf16_f32 v64, v58, v59
	v_add_co_u32_e32 v58, vcc, s77, v140
	v_lshl_add_u64 v[66:67], v[140:141], 0, s[80:81]
	s_nop 0
	v_addc_co_u32_e32 v59, vcc, 0, v141, vcc
	v_cvt_pk_bf16_f32 v65, v60, v61
	v_subrev_u32_e32 v218, s8, v58
	global_store_dwordx4 v218, v[62:65], s[8:9] sc1
	v_cvt_pk_bf16_f32 v50, v50, v51
	v_cvt_pk_bf16_f32 v51, v52, v53
	v_cvt_pk_bf16_f32 v52, v42, v43
	v_cvt_pk_bf16_f32 v53, v44, v45
	v_subrev_u32_e32 v218, s8, v66
	global_store_dwordx4 v218, v[50:53], s[8:9] offset:256 sc1
	v_cvt_pk_bf16_f32 v42, v54, v55
	v_cvt_pk_bf16_f32 v43, v56, v57
	v_cvt_pk_bf16_f32 v44, v46, v47
	v_add_co_u32_e32 v46, vcc, s87, v140
	s_nop 0
	v_lshl_add_u64 v[50:51], v[140:141], 0, s[88:89]
	v_addc_co_u32_e32 v47, vcc, 0, v141, vcc
	v_cvt_pk_bf16_f32 v45, v48, v49
	v_subrev_u32_e32 v218, s8, v46
	global_store_dwordx4 v218, v[42:45], s[8:9] sc1
	v_cvt_pk_bf16_f32 v34, v34, v35
	v_cvt_pk_bf16_f32 v35, v36, v37
	v_cvt_pk_bf16_f32 v36, v26, v27
	v_cvt_pk_bf16_f32 v37, v28, v29
	v_subrev_u32_e32 v218, s8, v50
	global_store_dwordx4 v218, v[34:37], s[8:9] offset:256 sc1
	v_cvt_pk_bf16_f32 v26, v38, v39
	v_cvt_pk_bf16_f32 v27, v40, v41
	v_cvt_pk_bf16_f32 v28, v30, v31
	v_add_co_u32_e32 v30, vcc, s94, v140
	s_nop 0
	v_lshl_add_u64 v[34:35], v[140:141], 0, s[90:91]
	v_addc_co_u32_e32 v31, vcc, 0, v141, vcc
	v_cvt_pk_bf16_f32 v29, v32, v33
	v_subrev_u32_e32 v218, s8, v30
	global_store_dwordx4 v218, v[26:29], s[8:9] sc1
	v_cvt_pk_bf16_f32 v18, v18, v19
	v_cvt_pk_bf16_f32 v19, v20, v21
	v_cvt_pk_bf16_f32 v20, v10, v11
	v_cvt_pk_bf16_f32 v21, v12, v13
	v_subrev_u32_e32 v218, s8, v34
	global_store_dwordx4 v218, v[18:21], s[8:9] offset:256 sc1
	v_cvt_pk_bf16_f32 v10, v22, v23
	v_cvt_pk_bf16_f32 v11, v24, v25
	v_cvt_pk_bf16_f32 v12, v14, v15
	v_add_co_u32_e32 v14, vcc, s95, v140
	s_nop 0
	v_lshl_add_u64 v[18:19], v[140:141], 0, s[92:93]
	v_addc_co_u32_e32 v15, vcc, 0, v141, vcc
	s_andn2_b64 vcc, exec, s[4:5]
	s_mov_b64 s[4:5], -1
	v_cvt_pk_bf16_f32 v13, v16, v17
	v_subrev_u32_e32 v218, s8, v14
	global_store_dwordx4 v218, v[10:13], s[8:9] sc1
	v_cvt_pk_bf16_f32 v6, v6, v7
	v_cvt_pk_bf16_f32 v7, v8, v9
	v_cvt_pk_bf16_f32 v8, v2, v3
	v_cvt_pk_bf16_f32 v9, v4, v5
	v_subrev_u32_e32 v218, s8, v18
	global_store_dwordx4 v218, v[6:9], s[8:9] offset:256 sc1
	s_cbranch_vccnz .LBB0_477
	s_andn2_b64 vcc, exec, s[6:7]
	s_cbranch_vccnz .LBB0_476
	s_barrier
	s_branch .LBB0_476

; __device__ __forceinline__ unsigned cvt_pk_bf16(float lo, float hi) { unsigned r; asm volatile("v_cvt_pk_bf16_f32 %0, %1, %2" : "=v"(r) : "v"(lo), "v"(hi)); return r; }
;     __device__ __forceinline__ void operator()(const f32x4 (&acc)[2][2][4][2], const Unit& u, int wr, int wc, int fr, int fq, const float (&rsv)[8]) const {
;     ...
;             for (int m = 0; m < 4; ++m) { bf16_t* rowp = O + (size_t)(row0 + ai * HALF + m * 16) * ldc + col0; float r[8]; const float rr = rsv[ai * 4 + m];
; #pragma unroll
;                 for (int n = 0; n < 2; ++n)
; #pragma unroll
;                     for (int j = 0; j < 4; ++j) { const float g = acc[ai][0][m][n][j] * rr, up = acc[ai][1][m][n][j] * rr;
;                         const float e = __builtin_amdgcn_exp2f(g * -1.4426950408889634f); r[n * 4 + j] = g * __builtin_amdgcn_rcpf(1.0f + e) * up; }
;                 u32x4 w; w.x = cvt_pk_bf16(r[0], r[1]); w.y = cvt_pk_bf16(r[2], r[3]); w.z = cvt_pk_bf16(r[4], r[5]); w.w = cvt_pk_bf16(r[6], r[7]);
;                 *(u32x4*)rowp = w; }
.LBB0_625:
	v_mov_b32_e32 v164, v126
	v_mov_b32_e32 v165, v122
	s_waitcnt vmcnt(8)
	v_pk_mul_f32 v[164:165], v[158:159], v[164:165] op_sel_hi:[0,1]
	v_mul_f32_e32 v122, 0xbfb8aa3b, v164
	v_exp_f32_e32 v122, v122
	v_lshl_or_b32 v160, s42, 7, v147
	v_ashrrev_i32_e32 v161, 31, v160
	v_mov_b64_e32 v[154:155], s[12:13]
	v_add_f32_e32 v122, 1.0, v122
	v_rcp_f32_e32 v122, v122
	v_mad_i64_i32 v[162:163], s[42:43], v142, s65, v[154:155]
	v_add_u32_e32 v143, 0x80, v142
	v_mul_f32_e32 v122, v164, v122
	v_mul_f32_e32 v126, v122, v165
	v_mov_b32_e32 v122, v127
	v_pk_mul_f32 v[122:123], v[158:159], v[122:123] op_sel_hi:[0,1]
	v_mul_f32_e32 v127, 0xbfb8aa3b, v122
	v_exp_f32_e32 v127, v127
	s_mov_b64 s[70:71], -1
	s_andn2_b64 vcc, exec, s[4:5]
	v_add_f32_e32 v127, 1.0, v127
	v_rcp_f32_e32 v127, v127
	s_nop 0
	v_mul_f32_e32 v122, v122, v127
	v_mul_f32_e32 v127, v122, v123
	v_mov_b32_e32 v122, v128
	v_mov_b32_e32 v123, v124
	v_pk_mul_f32 v[122:123], v[158:159], v[122:123] op_sel_hi:[0,1]
	v_mul_f32_e32 v124, 0xbfb8aa3b, v122
	v_exp_f32_e32 v124, v124
	s_nop 0
	v_add_f32_e32 v124, 1.0, v124
	v_rcp_f32_e32 v124, v124
	s_nop 0
	v_mul_f32_e32 v122, v122, v124
	v_mov_b32_e32 v124, v129
	v_mul_f32_e32 v128, v122, v123
	v_pk_mul_f32 v[122:123], v[158:159], v[124:125] op_sel_hi:[0,1]
	v_mul_f32_e32 v124, 0xbfb8aa3b, v122
	v_exp_f32_e32 v124, v124
	s_nop 0
	v_add_f32_e32 v124, 1.0, v124
	v_rcp_f32_e32 v124, v124
	s_nop 0
	v_mul_f32_e32 v122, v122, v124
	v_mul_f32_e32 v124, v122, v123
	v_mov_b32_e32 v122, v118
	v_mov_b32_e32 v123, v114
	v_pk_mul_f32 v[122:123], v[158:159], v[122:123] op_sel_hi:[0,1]
	v_mul_f32_e32 v114, 0xbfb8aa3b, v122
	v_exp_f32_e32 v114, v114
	s_nop 0
	v_add_f32_e32 v114, 1.0, v114
	v_rcp_f32_e32 v114, v114
	s_nop 0
	v_mul_f32_e32 v114, v122, v114
	v_mul_f32_e32 v118, v114, v123
	v_mov_b32_e32 v114, v119
	v_pk_mul_f32 v[114:115], v[158:159], v[114:115] op_sel_hi:[0,1]
	v_mul_f32_e32 v119, 0xbfb8aa3b, v114
	v_exp_f32_e32 v119, v119
	s_nop 0
	v_add_f32_e32 v119, 1.0, v119
	v_rcp_f32_e32 v119, v119
	s_nop 0
	v_mul_f32_e32 v114, v114, v119
	v_mul_f32_e32 v119, v114, v115
	v_mov_b32_e32 v114, v120
	v_mov_b32_e32 v115, v116
	v_pk_mul_f32 v[114:115], v[158:159], v[114:115] op_sel_hi:[0,1]
	v_mul_f32_e32 v116, 0xbfb8aa3b, v114
	v_exp_f32_e32 v116, v116
	s_nop 0
	v_add_f32_e32 v116, 1.0, v116
	v_rcp_f32_e32 v116, v116
	s_nop 0
	v_mul_f32_e32 v114, v114, v116
	v_mov_b32_e32 v116, v121
	v_mul_f32_e32 v122, v114, v115
	v_pk_mul_f32 v[114:115], v[158:159], v[116:117] op_sel_hi:[0,1]
	v_mul_f32_e32 v116, 0xbfb8aa3b, v114
	v_exp_f32_e32 v116, v116
	s_nop 0
	v_add_f32_e32 v116, 1.0, v116
	v_rcp_f32_e32 v116, v116
	s_nop 0
	v_mul_f32_e32 v114, v114, v116
	v_mul_f32_e32 v123, v114, v115
	v_lshlrev_b64 v[114:115], 1, v[160:161]
	v_lshl_add_u64 v[120:121], v[162:163], 0, v[114:115]
	v_cvt_pk_bf16_f32 v116, v126, v127
	v_cvt_pk_bf16_f32 v117, v128, v124
	v_cvt_pk_bf16_f32 v118, v118, v119
	v_cvt_pk_bf16_f32 v119, v122, v123
	v_subrev_u32_e32 v239, s12, v120
	global_store_dwordx4 v239, v[116:119], s[12:13] sc1
	s_nop 1
	v_mov_b32_e32 v118, v110
	v_mov_b32_e32 v119, v106
	v_pk_mul_f32 v[118:119], v[156:157], v[118:119] op_sel_hi:[0,1]
	v_mul_f32_e32 v106, 0xbfb8aa3b, v118
	v_exp_f32_e32 v106, v106
	v_or_b32_e32 v116, 16, v142
	v_mad_i64_i32 v[116:117], s[42:43], v116, s65, v[154:155]
	v_add_f32_e32 v106, 1.0, v106
	v_rcp_f32_e32 v106, v106
	s_nop 0
	v_mul_f32_e32 v106, v118, v106
	v_mul_f32_e32 v110, v106, v119
	v_mov_b32_e32 v106, v111
	v_pk_mul_f32 v[106:107], v[156:157], v[106:107] op_sel_hi:[0,1]
	v_mul_f32_e32 v111, 0xbfb8aa3b, v106
	v_exp_f32_e32 v111, v111
	s_nop 0
	v_add_f32_e32 v111, 1.0, v111
	v_rcp_f32_e32 v111, v111
	s_nop 0
	v_mul_f32_e32 v106, v106, v111
	v_mul_f32_e32 v111, v106, v107
	v_mov_b32_e32 v106, v112
	v_mov_b32_e32 v107, v108
	v_pk_mul_f32 v[106:107], v[156:157], v[106:107] op_sel_hi:[0,1]
	v_mul_f32_e32 v108, 0xbfb8aa3b, v106
	v_exp_f32_e32 v108, v108
	s_nop 0
	v_add_f32_e32 v108, 1.0, v108
	v_rcp_f32_e32 v108, v108
	s_nop 0
	v_mul_f32_e32 v106, v106, v108
	v_mov_b32_e32 v108, v113
	v_mul_f32_e32 v112, v106, v107
	v_pk_mul_f32 v[106:107], v[156:157], v[108:109] op_sel_hi:[0,1]
	v_mul_f32_e32 v108, 0xbfb8aa3b, v106
	v_exp_f32_e32 v108, v108
	s_nop 0
	v_add_f32_e32 v108, 1.0, v108
	v_rcp_f32_e32 v108, v108
	s_nop 0
	v_mul_f32_e32 v106, v106, v108
	v_mul_f32_e32 v108, v106, v107
	v_mov_b32_e32 v106, v102
	v_mov_b32_e32 v107, v98
	v_pk_mul_f32 v[106:107], v[156:157], v[106:107] op_sel_hi:[0,1]
	v_mul_f32_e32 v98, 0xbfb8aa3b, v106
	v_exp_f32_e32 v98, v98
	s_nop 0
	v_add_f32_e32 v98, 1.0, v98
	v_rcp_f32_e32 v98, v98
	s_nop 0
	v_mul_f32_e32 v98, v106, v98
	v_mul_f32_e32 v106, v98, v107
	v_mov_b32_e32 v98, v103
	v_pk_mul_f32 v[98:99], v[156:157], v[98:99] op_sel_hi:[0,1]
	v_mul_f32_e32 v102, 0xbfb8aa3b, v98
	v_exp_f32_e32 v102, v102
	s_nop 0
	v_add_f32_e32 v102, 1.0, v102
	v_rcp_f32_e32 v102, v102
	s_nop 0
	v_mul_f32_e32 v98, v98, v102
	v_mul_f32_e32 v107, v98, v99
	v_mov_b32_e32 v98, v104
	v_mov_b32_e32 v99, v100
	v_pk_mul_f32 v[98:99], v[156:157], v[98:99] op_sel_hi:[0,1]
	v_mul_f32_e32 v100, 0xbfb8aa3b, v98
	v_exp_f32_e32 v100, v100
	v_lshl_add_u64 v[102:103], v[116:117], 0, v[114:115]
	v_add_f32_e32 v100, 1.0, v100
	v_rcp_f32_e32 v100, v100
	s_nop 0
	v_mul_f32_e32 v98, v98, v100
	v_mov_b32_e32 v100, v105
	v_mul_f32_e32 v104, v98, v99
	v_pk_mul_f32 v[98:99], v[156:157], v[100:101] op_sel_hi:[0,1]
	v_mul_f32_e32 v100, 0xbfb8aa3b, v98
	v_exp_f32_e32 v100, v100
	s_nop 0
	v_add_f32_e32 v100, 1.0, v100
	v_rcp_f32_e32 v100, v100
	s_nop 0
	v_mul_f32_e32 v98, v98, v100
	v_mul_f32_e32 v101, v98, v99
	v_cvt_pk_bf16_f32 v98, v110, v111
	v_cvt_pk_bf16_f32 v99, v112, v108
; __device__ __forceinline__ unsigned cvt_pk_bf16(float lo, float hi) { unsigned r; asm volatile("v_cvt_pk_bf16_f32 %0, %1, %2" : "=v"(r) : "v"(lo), "v"(hi)); return r; }
;     __device__ __forceinline__ void operator()(const f32x4 (&acc)[2][2][4][2], const Unit& u, int wr, int wc, int fr, int fq, const float (&rsv)[8]) const {
;     ...
;             for (int m = 0; m < 4; ++m) { bf16_t* rowp = O + (size_t)(row0 + ai * HALF + m * 16) * ldc + col0; float r[8]; const float rr = rsv[ai * 4 + m];
; #pragma unroll
;                 for (int n = 0; n < 2; ++n)
; #pragma unroll
;                     for (int j = 0; j < 4; ++j) { const float g = acc[ai][0][m][n][j] * rr, up = acc[ai][1][m][n][j] * rr;
;                         const float e = __builtin_amdgcn_exp2f(g * -1.4426950408889634f); r[n * 4 + j] = g * __builtin_amdgcn_rcpf(1.0f + e) * up; }
;                 u32x4 w; w.x = cvt_pk_bf16(r[0], r[1]); w.y = cvt_pk_bf16(r[2], r[3]); w.z = cvt_pk_bf16(r[4], r[5]); w.w = cvt_pk_bf16(r[6], r[7]);
;                 *(u32x4*)rowp = w; }
	v_cvt_pk_bf16_f32 v100, v106, v107
	v_cvt_pk_bf16_f32 v101, v104, v101
	v_subrev_u32_e32 v239, s12, v102
	global_store_dwordx4 v239, v[98:101], s[12:13] sc1
	s_nop 1
	v_mov_b32_e32 v100, v94
	v_mov_b32_e32 v101, v90
	v_pk_mul_f32 v[100:101], v[152:153], v[100:101] op_sel_hi:[0,1]
	v_mul_f32_e32 v90, 0xbfb8aa3b, v100
	v_exp_f32_e32 v90, v90
	v_or_b32_e32 v98, 32, v142
	v_mad_i64_i32 v[98:99], s[42:43], v98, s65, v[154:155]
	v_add_f32_e32 v90, 1.0, v90
	v_rcp_f32_e32 v90, v90
	s_nop 0
	v_mul_f32_e32 v90, v100, v90
	v_mul_f32_e32 v94, v90, v101
	v_mov_b32_e32 v90, v95
	v_pk_mul_f32 v[90:91], v[152:153], v[90:91] op_sel_hi:[0,1]
	v_mul_f32_e32 v95, 0xbfb8aa3b, v90
	v_exp_f32_e32 v95, v95
	s_nop 0
	v_add_f32_e32 v95, 1.0, v95
	v_rcp_f32_e32 v95, v95
	s_nop 0
	v_mul_f32_e32 v90, v90, v95
	v_mul_f32_e32 v95, v90, v91
	v_mov_b32_e32 v90, v96
	v_mov_b32_e32 v91, v92
	v_pk_mul_f32 v[90:91], v[152:153], v[90:91] op_sel_hi:[0,1]
	v_mul_f32_e32 v92, 0xbfb8aa3b, v90
	v_exp_f32_e32 v92, v92
	s_nop 0
	v_add_f32_e32 v92, 1.0, v92
	v_rcp_f32_e32 v92, v92
	s_nop 0
	v_mul_f32_e32 v90, v90, v92
	v_mov_b32_e32 v92, v97
	v_mul_f32_e32 v96, v90, v91
	v_pk_mul_f32 v[90:91], v[152:153], v[92:93] op_sel_hi:[0,1]
	v_mul_f32_e32 v92, 0xbfb8aa3b, v90
	v_exp_f32_e32 v92, v92
	s_nop 0
	v_add_f32_e32 v92, 1.0, v92
	v_rcp_f32_e32 v92, v92
	s_nop 0
	v_mul_f32_e32 v90, v90, v92
	v_mul_f32_e32 v92, v90, v91
	v_mov_b32_e32 v90, v86
	v_mov_b32_e32 v91, v82
	v_pk_mul_f32 v[90:91], v[152:153], v[90:91] op_sel_hi:[0,1]
	v_mul_f32_e32 v82, 0xbfb8aa3b, v90
	v_exp_f32_e32 v82, v82
	s_nop 0
	v_add_f32_e32 v82, 1.0, v82
	v_rcp_f32_e32 v82, v82
	s_nop 0
	v_mul_f32_e32 v82, v90, v82
	v_mul_f32_e32 v90, v82, v91
	v_mov_b32_e32 v82, v87
	v_pk_mul_f32 v[82:83], v[152:153], v[82:83] op_sel_hi:[0,1]
	v_mul_f32_e32 v86, 0xbfb8aa3b, v82
	v_exp_f32_e32 v86, v86
	s_nop 0
	v_add_f32_e32 v86, 1.0, v86
	v_rcp_f32_e32 v86, v86
	s_nop 0
	v_mul_f32_e32 v82, v82, v86
	v_mul_f32_e32 v91, v82, v83
	v_mov_b32_e32 v82, v88
	v_mov_b32_e32 v83, v84
	v_pk_mul_f32 v[82:83], v[152:153], v[82:83] op_sel_hi:[0,1]
	v_mul_f32_e32 v84, 0xbfb8aa3b, v82
	v_exp_f32_e32 v84, v84
	v_lshl_add_u64 v[86:87], v[98:99], 0, v[114:115]
	v_add_f32_e32 v84, 1.0, v84
	v_rcp_f32_e32 v84, v84
	s_nop 0
	v_mul_f32_e32 v82, v82, v84
	v_mov_b32_e32 v84, v89
	v_mul_f32_e32 v88, v82, v83
	v_pk_mul_f32 v[82:83], v[152:153], v[84:85] op_sel_hi:[0,1]
	v_mul_f32_e32 v84, 0xbfb8aa3b, v82
	v_exp_f32_e32 v84, v84
	s_nop 0
	v_add_f32_e32 v84, 1.0, v84
	v_rcp_f32_e32 v84, v84
	s_nop 0
	v_mul_f32_e32 v82, v82, v84
	v_mul_f32_e32 v85, v82, v83
	v_cvt_pk_bf16_f32 v82, v94, v95
	v_cvt_pk_bf16_f32 v83, v96, v92
	v_cvt_pk_bf16_f32 v84, v90, v91
	v_cvt_pk_bf16_f32 v85, v88, v85
	v_subrev_u32_e32 v239, s12, v86
	global_store_dwordx4 v239, v[82:85], s[12:13] sc1
	s_nop 1
	v_mov_b32_e32 v84, v78
	v_mov_b32_e32 v85, v74
	v_pk_mul_f32 v[84:85], v[150:151], v[84:85] op_sel_hi:[0,1]
	v_mul_f32_e32 v74, 0xbfb8aa3b, v84
	v_exp_f32_e32 v74, v74
	v_or_b32_e32 v82, 48, v142
	v_mad_i64_i32 v[82:83], s[42:43], v82, s65, v[154:155]
	v_add_f32_e32 v74, 1.0, v74
	v_rcp_f32_e32 v74, v74
	s_nop 0
	v_mul_f32_e32 v74, v84, v74
	v_mul_f32_e32 v78, v74, v85
	v_mov_b32_e32 v74, v79
	v_pk_mul_f32 v[74:75], v[150:151], v[74:75] op_sel_hi:[0,1]
	v_mul_f32_e32 v79, 0xbfb8aa3b, v74
	v_exp_f32_e32 v79, v79
	s_nop 0
	v_add_f32_e32 v79, 1.0, v79
	v_rcp_f32_e32 v79, v79
	s_nop 0
	v_mul_f32_e32 v74, v74, v79
	v_mul_f32_e32 v79, v74, v75
	v_mov_b32_e32 v74, v80
	v_mov_b32_e32 v75, v76
	v_pk_mul_f32 v[74:75], v[150:151], v[74:75] op_sel_hi:[0,1]
	v_mul_f32_e32 v76, 0xbfb8aa3b, v74
	v_exp_f32_e32 v76, v76
	s_nop 0
	v_add_f32_e32 v76, 1.0, v76
	v_rcp_f32_e32 v76, v76
	s_nop 0
	v_mul_f32_e32 v74, v74, v76
	v_mov_b32_e32 v76, v81
	v_mul_f32_e32 v80, v74, v75
	v_pk_mul_f32 v[74:75], v[150:151], v[76:77] op_sel_hi:[0,1]
	v_mul_f32_e32 v76, 0xbfb8aa3b, v74
	v_exp_f32_e32 v76, v76
	s_nop 0
	v_add_f32_e32 v76, 1.0, v76
	v_rcp_f32_e32 v76, v76
	s_nop 0
	v_mul_f32_e32 v74, v74, v76
	v_mul_f32_e32 v76, v74, v75
	v_mov_b32_e32 v74, v70
	v_mov_b32_e32 v75, v66
	v_pk_mul_f32 v[74:75], v[150:151], v[74:75] op_sel_hi:[0,1]
	v_mul_f32_e32 v66, 0xbfb8aa3b, v74
	v_exp_f32_e32 v66, v66
	s_nop 0
	v_add_f32_e32 v66, 1.0, v66
	v_rcp_f32_e32 v66, v66
	s_nop 0
	v_mul_f32_e32 v66, v74, v66
	v_mul_f32_e32 v74, v66, v75
	v_mov_b32_e32 v66, v71
	v_pk_mul_f32 v[66:67], v[150:151], v[66:67] op_sel_hi:[0,1]
	v_mul_f32_e32 v70, 0xbfb8aa3b, v66
	v_exp_f32_e32 v70, v70
	s_nop 0
	v_add_f32_e32 v70, 1.0, v70
	v_rcp_f32_e32 v70, v70
	s_nop 0
	v_mul_f32_e32 v66, v66, v70
	v_mul_f32_e32 v75, v66, v67
	v_mov_b32_e32 v66, v72
	v_mov_b32_e32 v67, v68
	v_pk_mul_f32 v[66:67], v[150:151], v[66:67] op_sel_hi:[0,1]
	v_mul_f32_e32 v68, 0xbfb8aa3b, v66
	v_exp_f32_e32 v68, v68
	v_lshl_add_u64 v[70:71], v[82:83], 0, v[114:115]
	v_add_f32_e32 v68, 1.0, v68
	v_rcp_f32_e32 v68, v68
	s_nop 0
	v_mul_f32_e32 v66, v66, v68
	v_mov_b32_e32 v68, v73
	v_mul_f32_e32 v72, v66, v67
	v_pk_mul_f32 v[66:67], v[150:151], v[68:69] op_sel_hi:[0,1]
	v_mul_f32_e32 v68, 0xbfb8aa3b, v66
	v_exp_f32_e32 v68, v68
	s_nop 0
	v_add_f32_e32 v68, 1.0, v68
	v_rcp_f32_e32 v68, v68
	s_nop 0
	v_mul_f32_e32 v66, v66, v68
	v_mul_f32_e32 v69, v66, v67
	v_cvt_pk_bf16_f32 v66, v78, v79
	v_cvt_pk_bf16_f32 v67, v80, v76
	v_cvt_pk_bf16_f32 v68, v74, v75
	v_cvt_pk_bf16_f32 v69, v72, v69
	v_subrev_u32_e32 v239, s12, v70
	global_store_dwordx4 v239, v[66:69], s[12:13] sc1
	s_nop 1
	v_mov_b32_e32 v68, v62
	v_mov_b32_e32 v69, v58
	v_pk_mul_f32 v[68:69], v[148:149], v[68:69] op_sel_hi:[0,1]
	v_mul_f32_e32 v58, 0xbfb8aa3b, v68
	v_exp_f32_e32 v58, v58
	v_mad_i64_i32 v[66:67], s[42:43], v143, s65, v[154:155]
; __device__ __forceinline__ unsigned cvt_pk_bf16(float lo, float hi) { unsigned r; asm volatile("v_cvt_pk_bf16_f32 %0, %1, %2" : "=v"(r) : "v"(lo), "v"(hi)); return r; }
;     __device__ __forceinline__ void operator()(const f32x4 (&acc)[2][2][4][2], const Unit& u, int wr, int wc, int fr, int fq, const float (&rsv)[8]) const {
;     ...
;             for (int m = 0; m < 4; ++m) { bf16_t* rowp = O + (size_t)(row0 + ai * HALF + m * 16) * ldc + col0; float r[8]; const float rr = rsv[ai * 4 + m];
; #pragma unroll
;                 for (int n = 0; n < 2; ++n)
; #pragma unroll
;                     for (int j = 0; j < 4; ++j) { const float g = acc[ai][0][m][n][j] * rr, up = acc[ai][1][m][n][j] * rr;
;                         const float e = __builtin_amdgcn_exp2f(g * -1.4426950408889634f); r[n * 4 + j] = g * __builtin_amdgcn_rcpf(1.0f + e) * up; }
;                 u32x4 w; w.x = cvt_pk_bf16(r[0], r[1]); w.y = cvt_pk_bf16(r[2], r[3]); w.z = cvt_pk_bf16(r[4], r[5]); w.w = cvt_pk_bf16(r[6], r[7]);
;                 *(u32x4*)rowp = w; }
	v_add_f32_e32 v58, 1.0, v58
	v_rcp_f32_e32 v58, v58
	s_nop 0
	v_mul_f32_e32 v58, v68, v58
	v_mul_f32_e32 v62, v58, v69
	v_mov_b32_e32 v58, v63
	v_pk_mul_f32 v[58:59], v[148:149], v[58:59] op_sel_hi:[0,1]
	v_mul_f32_e32 v63, 0xbfb8aa3b, v58
	v_exp_f32_e32 v63, v63
	s_nop 0
	v_add_f32_e32 v63, 1.0, v63
	v_rcp_f32_e32 v63, v63
	s_nop 0
	v_mul_f32_e32 v58, v58, v63
	v_mul_f32_e32 v63, v58, v59
	v_mov_b32_e32 v58, v64
	v_mov_b32_e32 v59, v60
	v_pk_mul_f32 v[58:59], v[148:149], v[58:59] op_sel_hi:[0,1]
	v_mul_f32_e32 v60, 0xbfb8aa3b, v58
	v_exp_f32_e32 v60, v60
	s_nop 0
	v_add_f32_e32 v60, 1.0, v60
	v_rcp_f32_e32 v60, v60
	s_nop 0
	v_mul_f32_e32 v58, v58, v60
	v_mov_b32_e32 v60, v65
	v_mul_f32_e32 v64, v58, v59
	v_pk_mul_f32 v[58:59], v[148:149], v[60:61] op_sel_hi:[0,1]
	v_mul_f32_e32 v60, 0xbfb8aa3b, v58
	v_exp_f32_e32 v60, v60
	s_nop 0
	v_add_f32_e32 v60, 1.0, v60
	v_rcp_f32_e32 v60, v60
	s_nop 0
	v_mul_f32_e32 v58, v58, v60
	v_mul_f32_e32 v60, v58, v59
	v_mov_b32_e32 v58, v54
	v_mov_b32_e32 v59, v50
	v_pk_mul_f32 v[58:59], v[148:149], v[58:59] op_sel_hi:[0,1]
	v_mul_f32_e32 v50, 0xbfb8aa3b, v58
	v_exp_f32_e32 v50, v50
	s_nop 0
	v_add_f32_e32 v50, 1.0, v50
	v_rcp_f32_e32 v50, v50
	s_nop 0
	v_mul_f32_e32 v50, v58, v50
	v_mul_f32_e32 v58, v50, v59
	v_mov_b32_e32 v50, v55
	v_pk_mul_f32 v[50:51], v[148:149], v[50:51] op_sel_hi:[0,1]
	v_mul_f32_e32 v54, 0xbfb8aa3b, v50
	v_exp_f32_e32 v54, v54
	s_nop 0
	v_add_f32_e32 v54, 1.0, v54
	v_rcp_f32_e32 v54, v54
	s_nop 0
	v_mul_f32_e32 v50, v50, v54
	v_mul_f32_e32 v59, v50, v51
	v_mov_b32_e32 v50, v56
	v_mov_b32_e32 v51, v52
	v_pk_mul_f32 v[50:51], v[148:149], v[50:51] op_sel_hi:[0,1]
	v_mul_f32_e32 v52, 0xbfb8aa3b, v50
	v_exp_f32_e32 v52, v52
	v_lshl_add_u64 v[54:55], v[66:67], 0, v[114:115]
	v_add_f32_e32 v52, 1.0, v52
	v_rcp_f32_e32 v52, v52
	s_nop 0
	v_mul_f32_e32 v50, v50, v52
	v_mov_b32_e32 v52, v57
	v_mul_f32_e32 v56, v50, v51
	v_pk_mul_f32 v[50:51], v[148:149], v[52:53] op_sel_hi:[0,1]
	v_mul_f32_e32 v52, 0xbfb8aa3b, v50
	v_exp_f32_e32 v52, v52
	s_nop 0
	v_add_f32_e32 v52, 1.0, v52
	v_rcp_f32_e32 v52, v52
	s_nop 0
	v_mul_f32_e32 v50, v50, v52
	v_mul_f32_e32 v53, v50, v51
	v_cvt_pk_bf16_f32 v50, v62, v63
	v_cvt_pk_bf16_f32 v51, v64, v60
	v_cvt_pk_bf16_f32 v52, v58, v59
	v_cvt_pk_bf16_f32 v53, v56, v53
	v_subrev_u32_e32 v239, s12, v54
	global_store_dwordx4 v239, v[50:53], s[12:13] sc1
	s_nop 1
	v_mov_b32_e32 v52, v46
	v_mov_b32_e32 v53, v42
	v_pk_mul_f32 v[52:53], v[146:147], v[52:53] op_sel_hi:[0,1]
	v_mul_f32_e32 v42, 0xbfb8aa3b, v52
	v_exp_f32_e32 v42, v42
	v_add_u32_e32 v50, 0x90, v142
	v_mad_i64_i32 v[50:51], s[42:43], v50, s65, v[154:155]
	v_add_f32_e32 v42, 1.0, v42
	v_rcp_f32_e32 v42, v42
	s_nop 0
	v_mul_f32_e32 v42, v52, v42
	v_mul_f32_e32 v46, v42, v53
	v_mov_b32_e32 v42, v47
	v_pk_mul_f32 v[42:43], v[146:147], v[42:43] op_sel_hi:[0,1]
	v_mul_f32_e32 v47, 0xbfb8aa3b, v42
	v_exp_f32_e32 v47, v47
	s_nop 0
	v_add_f32_e32 v47, 1.0, v47
	v_rcp_f32_e32 v47, v47
	s_nop 0
	v_mul_f32_e32 v42, v42, v47
	v_mul_f32_e32 v47, v42, v43
	v_mov_b32_e32 v42, v48
	v_mov_b32_e32 v43, v44
	v_pk_mul_f32 v[42:43], v[146:147], v[42:43] op_sel_hi:[0,1]
	v_mul_f32_e32 v44, 0xbfb8aa3b, v42
	v_exp_f32_e32 v44, v44
	s_nop 0
	v_add_f32_e32 v44, 1.0, v44
	v_rcp_f32_e32 v44, v44
	s_nop 0
	v_mul_f32_e32 v42, v42, v44
	v_mov_b32_e32 v44, v49
	v_mul_f32_e32 v48, v42, v43
	v_pk_mul_f32 v[42:43], v[146:147], v[44:45] op_sel_hi:[0,1]
	v_mul_f32_e32 v44, 0xbfb8aa3b, v42
	v_exp_f32_e32 v44, v44
	s_nop 0
	v_add_f32_e32 v44, 1.0, v44
	v_rcp_f32_e32 v44, v44
	s_nop 0
	v_mul_f32_e32 v42, v42, v44
	v_mul_f32_e32 v44, v42, v43
	v_mov_b32_e32 v42, v38
	v_mov_b32_e32 v43, v34
	v_pk_mul_f32 v[42:43], v[146:147], v[42:43] op_sel_hi:[0,1]
	v_mul_f32_e32 v34, 0xbfb8aa3b, v42
	v_exp_f32_e32 v34, v34
	s_nop 0
	v_add_f32_e32 v34, 1.0, v34
	v_rcp_f32_e32 v34, v34
	s_nop 0
	v_mul_f32_e32 v34, v42, v34
	v_mul_f32_e32 v42, v34, v43
	v_mov_b32_e32 v34, v39
	v_pk_mul_f32 v[34:35], v[146:147], v[34:35] op_sel_hi:[0,1]
	v_mul_f32_e32 v38, 0xbfb8aa3b, v34
	v_exp_f32_e32 v38, v38
	s_nop 0
	v_add_f32_e32 v38, 1.0, v38
	v_rcp_f32_e32 v38, v38
	s_nop 0
	v_mul_f32_e32 v34, v34, v38
	v_mul_f32_e32 v43, v34, v35
	v_mov_b32_e32 v34, v40
	v_mov_b32_e32 v35, v36
	v_pk_mul_f32 v[34:35], v[146:147], v[34:35] op_sel_hi:[0,1]
	v_mul_f32_e32 v36, 0xbfb8aa3b, v34
	v_exp_f32_e32 v36, v36
	v_lshl_add_u64 v[38:39], v[50:51], 0, v[114:115]
	v_add_f32_e32 v36, 1.0, v36
	v_rcp_f32_e32 v36, v36
	s_nop 0
	v_mul_f32_e32 v34, v34, v36
	v_mov_b32_e32 v36, v41
	v_mul_f32_e32 v40, v34, v35
	v_pk_mul_f32 v[34:35], v[146:147], v[36:37] op_sel_hi:[0,1]
	v_mul_f32_e32 v36, 0xbfb8aa3b, v34
	v_exp_f32_e32 v36, v36
	s_nop 0
	v_add_f32_e32 v36, 1.0, v36
	v_rcp_f32_e32 v36, v36
	s_nop 0
	v_mul_f32_e32 v34, v34, v36
	v_mul_f32_e32 v37, v34, v35
	v_cvt_pk_bf16_f32 v34, v46, v47
	v_cvt_pk_bf16_f32 v35, v48, v44
	v_cvt_pk_bf16_f32 v36, v42, v43
	v_cvt_pk_bf16_f32 v37, v40, v37
	v_subrev_u32_e32 v239, s12, v38
	global_store_dwordx4 v239, v[34:37], s[12:13] sc1
	s_nop 1
	v_mov_b32_e32 v36, v30
	v_mov_b32_e32 v37, v26
	v_pk_mul_f32 v[36:37], v[144:145], v[36:37] op_sel_hi:[0,1]
	v_mul_f32_e32 v26, 0xbfb8aa3b, v36
; __device__ __forceinline__ unsigned cvt_pk_bf16(float lo, float hi) { unsigned r; asm volatile("v_cvt_pk_bf16_f32 %0, %1, %2" : "=v"(r) : "v"(lo), "v"(hi)); return r; }
;     __device__ __forceinline__ void operator()(const f32x4 (&acc)[2][2][4][2], const Unit& u, int wr, int wc, int fr, int fq, const float (&rsv)[8]) const {
;     ...
;             for (int m = 0; m < 4; ++m) { bf16_t* rowp = O + (size_t)(row0 + ai * HALF + m * 16) * ldc + col0; float r[8]; const float rr = rsv[ai * 4 + m];
; #pragma unroll
;                 for (int n = 0; n < 2; ++n)
; #pragma unroll
;                     for (int j = 0; j < 4; ++j) { const float g = acc[ai][0][m][n][j] * rr, up = acc[ai][1][m][n][j] * rr;
;                         const float e = __builtin_amdgcn_exp2f(g * -1.4426950408889634f); r[n * 4 + j] = g * __builtin_amdgcn_rcpf(1.0f + e) * up; }
;                 u32x4 w; w.x = cvt_pk_bf16(r[0], r[1]); w.y = cvt_pk_bf16(r[2], r[3]); w.z = cvt_pk_bf16(r[4], r[5]); w.w = cvt_pk_bf16(r[6], r[7]);
;                 *(u32x4*)rowp = w; }
	v_exp_f32_e32 v26, v26
	v_add_u32_e32 v34, 0xa0, v142
	v_mad_i64_i32 v[34:35], s[42:43], v34, s65, v[154:155]
	v_add_f32_e32 v26, 1.0, v26
	v_rcp_f32_e32 v26, v26
	s_nop 0
	v_mul_f32_e32 v26, v36, v26
	v_mul_f32_e32 v30, v26, v37
	v_mov_b32_e32 v26, v31
	v_pk_mul_f32 v[26:27], v[144:145], v[26:27] op_sel_hi:[0,1]
	v_mul_f32_e32 v31, 0xbfb8aa3b, v26
	v_exp_f32_e32 v31, v31
	s_nop 0
	v_add_f32_e32 v31, 1.0, v31
	v_rcp_f32_e32 v31, v31
	s_nop 0
	v_mul_f32_e32 v26, v26, v31
	v_mul_f32_e32 v31, v26, v27
	v_mov_b32_e32 v26, v32
	v_mov_b32_e32 v27, v28
	v_pk_mul_f32 v[26:27], v[144:145], v[26:27] op_sel_hi:[0,1]
	v_mul_f32_e32 v28, 0xbfb8aa3b, v26
	v_exp_f32_e32 v28, v28
	s_nop 0
	v_add_f32_e32 v28, 1.0, v28
	v_rcp_f32_e32 v28, v28
	s_nop 0
	v_mul_f32_e32 v26, v26, v28
	v_mov_b32_e32 v28, v33
	v_mul_f32_e32 v32, v26, v27
	v_pk_mul_f32 v[26:27], v[144:145], v[28:29] op_sel_hi:[0,1]
	v_mul_f32_e32 v28, 0xbfb8aa3b, v26
	v_exp_f32_e32 v28, v28
	s_nop 0
	v_add_f32_e32 v28, 1.0, v28
	v_rcp_f32_e32 v28, v28
	s_nop 0
	v_mul_f32_e32 v26, v26, v28
	v_mul_f32_e32 v28, v26, v27
	v_mov_b32_e32 v26, v22
	v_mov_b32_e32 v27, v18
	v_pk_mul_f32 v[26:27], v[144:145], v[26:27] op_sel_hi:[0,1]
	v_mul_f32_e32 v18, 0xbfb8aa3b, v26
	v_exp_f32_e32 v18, v18
	s_nop 0
	v_add_f32_e32 v18, 1.0, v18
	v_rcp_f32_e32 v18, v18
	s_nop 0
	v_mul_f32_e32 v18, v26, v18
	v_mul_f32_e32 v26, v18, v27
	v_mov_b32_e32 v18, v23
	v_pk_mul_f32 v[18:19], v[144:145], v[18:19] op_sel_hi:[0,1]
	v_mul_f32_e32 v22, 0xbfb8aa3b, v18
	v_exp_f32_e32 v22, v22
	s_nop 0
	v_add_f32_e32 v22, 1.0, v22
	v_rcp_f32_e32 v22, v22
	s_nop 0
	v_mul_f32_e32 v18, v18, v22
	v_mul_f32_e32 v27, v18, v19
	v_mov_b32_e32 v18, v24
	v_mov_b32_e32 v19, v20
	v_pk_mul_f32 v[18:19], v[144:145], v[18:19] op_sel_hi:[0,1]
	v_mul_f32_e32 v20, 0xbfb8aa3b, v18
	v_exp_f32_e32 v20, v20
	v_lshl_add_u64 v[22:23], v[34:35], 0, v[114:115]
	v_add_f32_e32 v20, 1.0, v20
	v_rcp_f32_e32 v20, v20
	s_nop 0
	v_mul_f32_e32 v18, v18, v20
	v_mov_b32_e32 v20, v25
	v_mul_f32_e32 v24, v18, v19
	v_pk_mul_f32 v[18:19], v[144:145], v[20:21] op_sel_hi:[0,1]
	v_mul_f32_e32 v20, 0xbfb8aa3b, v18
	v_exp_f32_e32 v20, v20
	s_nop 0
	v_add_f32_e32 v20, 1.0, v20
	v_rcp_f32_e32 v20, v20
	s_nop 0
	v_mul_f32_e32 v18, v18, v20
	v_mul_f32_e32 v21, v18, v19
	v_cvt_pk_bf16_f32 v18, v30, v31
	v_cvt_pk_bf16_f32 v19, v32, v28
	v_cvt_pk_bf16_f32 v20, v26, v27
	v_cvt_pk_bf16_f32 v21, v24, v21
	v_subrev_u32_e32 v239, s12, v22
	global_store_dwordx4 v239, v[18:21], s[12:13] sc1
	s_nop 1
	v_mov_b32_e32 v20, v14
	v_mov_b32_e32 v21, v10
	v_pk_mul_f32 v[20:21], v[140:141], v[20:21] op_sel_hi:[0,1]
	v_mul_f32_e32 v10, 0xbfb8aa3b, v20
	v_exp_f32_e32 v10, v10
	v_add_u32_e32 v18, 0xb0, v142
	v_mad_i64_i32 v[18:19], s[42:43], v18, s65, v[154:155]
	v_add_f32_e32 v10, 1.0, v10
	v_rcp_f32_e32 v10, v10
	s_nop 0
	v_mul_f32_e32 v10, v20, v10
	v_mul_f32_e32 v14, v10, v21
	v_mov_b32_e32 v10, v15
	v_pk_mul_f32 v[10:11], v[140:141], v[10:11] op_sel_hi:[0,1]
	v_mul_f32_e32 v15, 0xbfb8aa3b, v10
	v_exp_f32_e32 v15, v15
	s_nop 0
	v_add_f32_e32 v15, 1.0, v15
	v_rcp_f32_e32 v15, v15
	s_nop 0
	v_mul_f32_e32 v10, v10, v15
	v_mul_f32_e32 v15, v10, v11
	v_mov_b32_e32 v10, v16
	v_mov_b32_e32 v11, v12
	v_pk_mul_f32 v[10:11], v[140:141], v[10:11] op_sel_hi:[0,1]
	v_mul_f32_e32 v12, 0xbfb8aa3b, v10
	v_exp_f32_e32 v12, v12
	s_nop 0
	v_add_f32_e32 v12, 1.0, v12
	v_rcp_f32_e32 v12, v12
	s_nop 0
	v_mul_f32_e32 v10, v10, v12
	v_mov_b32_e32 v12, v17
	v_mul_f32_e32 v16, v10, v11
	v_pk_mul_f32 v[10:11], v[140:141], v[12:13] op_sel_hi:[0,1]
	v_mul_f32_e32 v12, 0xbfb8aa3b, v10
	v_exp_f32_e32 v12, v12
	s_nop 0
	v_add_f32_e32 v12, 1.0, v12
	v_rcp_f32_e32 v12, v12
	s_nop 0
	v_mul_f32_e32 v10, v10, v12
	v_mul_f32_e32 v12, v10, v11
	v_mov_b32_e32 v10, v6
	v_mov_b32_e32 v11, v2
	v_pk_mul_f32 v[10:11], v[140:141], v[10:11] op_sel_hi:[0,1]
	v_mul_f32_e32 v2, 0xbfb8aa3b, v10
	v_exp_f32_e32 v2, v2
	s_nop 0
	v_add_f32_e32 v2, 1.0, v2
	v_rcp_f32_e32 v2, v2
	s_nop 0
	v_mul_f32_e32 v2, v10, v2
	v_mul_f32_e32 v10, v2, v11
	v_mov_b32_e32 v2, v7
	v_pk_mul_f32 v[2:3], v[140:141], v[2:3] op_sel_hi:[0,1]
	v_mul_f32_e32 v6, 0xbfb8aa3b, v2
	v_exp_f32_e32 v6, v6
	s_nop 0
	v_add_f32_e32 v6, 1.0, v6
	v_rcp_f32_e32 v6, v6
	s_nop 0
	v_mul_f32_e32 v2, v2, v6
	v_mul_f32_e32 v11, v2, v3
	v_mov_b32_e32 v2, v8
	v_mov_b32_e32 v3, v4
	v_pk_mul_f32 v[2:3], v[140:141], v[2:3] op_sel_hi:[0,1]
	v_mul_f32_e32 v4, 0xbfb8aa3b, v2
	v_exp_f32_e32 v4, v4
	v_lshl_add_u64 v[6:7], v[18:19], 0, v[114:115]
	v_add_f32_e32 v4, 1.0, v4
	v_rcp_f32_e32 v4, v4
	s_nop 0
	v_mul_f32_e32 v2, v2, v4
	v_mov_b32_e32 v4, v9
	v_mul_f32_e32 v8, v2, v3
	v_pk_mul_f32 v[2:3], v[140:141], v[4:5] op_sel_hi:[0,1]
	v_mul_f32_e32 v4, 0xbfb8aa3b, v2
	v_exp_f32_e32 v4, v4
	s_nop 0
	v_add_f32_e32 v4, 1.0, v4
	v_rcp_f32_e32 v4, v4
	s_nop 0
	v_mul_f32_e32 v2, v2, v4
	v_mul_f32_e32 v5, v2, v3
	v_cvt_pk_bf16_f32 v2, v14, v15
	v_cvt_pk_bf16_f32 v3, v16, v12
	v_cvt_pk_bf16_f32 v4, v10, v11
	v_cvt_pk_bf16_f32 v5, v8, v5
	v_subrev_u32_e32 v239, s12, v6
	global_store_dwordx4 v239, v[2:5], s[12:13] sc1
	s_cbranch_vccnz .LBB0_618
	s_andn2_b64 vcc, exec, s[10:11]
	s_cbranch_vccnz .LBB0_617
	s_barrier
	s_branch .LBB0_617

; __device__ __forceinline__ unsigned cvt_pk_bf16(float lo, float hi) { unsigned r; asm volatile("v_cvt_pk_bf16_f32 %0, %1, %2" : "=v"(r) : "v"(lo), "v"(hi)); return r; }
;     __device__ __forceinline__ void operator()(const f32x4 (&acc)[2][2][4][2], const Unit& u, int wr, int wc, int fr, int fq, const float (&rsv)[8]) const {
;     ...
;             for (int m = 0; m < 4; ++m) { bf16_t* rowp = O + (size_t)(row0 + ai * HALF + m * 16) * ldc + col0;
; #pragma unroll
;                 for (int bj = 0; bj < 2; ++bj) { const f32x4 v0 = acc[ai][bj][m][0], v1 = acc[ai][bj][m][1];
;                     u32x4 w; w.x = cvt_pk_bf16(v0[0], v0[1]); w.y = cvt_pk_bf16(v0[2], v0[3]); w.z = cvt_pk_bf16(v1[0], v1[1]); w.w = cvt_pk_bf16(v1[2], v1[3]);
;                     *(u32x4*)(rowp + bj * HALF) = w; } }
.LBB0_706:
	v_lshl_add_u32 v146, s60, 8, v142
	v_lshl_or_b32 v140, s61, 8, v144
	v_ashrrev_i32_e32 v147, 31, v146
	v_ashrrev_i32_e32 v141, 31, v140
	v_lshlrev_b64 v[148:149], 11, v[146:147]
	v_lshl_add_u64 v[148:149], s[12:13], 0, v[148:149]
	v_lshlrev_b64 v[150:151], 1, v[140:141]
	v_lshl_add_u64 v[140:141], v[148:149], 0, v[150:151]
	v_cvt_pk_bf16_f32 v126, v126, v127
	v_cvt_pk_bf16_f32 v127, v128, v129
	v_cvt_pk_bf16_f32 v128, v122, v123
	v_cvt_pk_bf16_f32 v129, v124, v125
	v_subrev_u32_e32 v218, s12, v140
	global_store_dwordx4 v218, v[126:129], s[12:13] sc1
	v_cvt_pk_bf16_f32 v114, v114, v115
	v_cvt_pk_bf16_f32 v115, v116, v117
	v_cvt_pk_bf16_f32 v116, v106, v107
	v_or_b32_e32 v106, 16, v146
	v_ashrrev_i32_e32 v107, 31, v106
	v_lshlrev_b64 v[106:107], 11, v[106:107]
	v_lshl_add_u64 v[106:107], s[12:13], 0, v[106:107]
	v_cvt_pk_bf16_f32 v117, v108, v109
	v_subrev_u32_e32 v218, s12, v140
	global_store_dwordx4 v218, v[114:117], s[12:13] offset:256 sc1
	s_nop 1
	v_lshl_add_u64 v[114:115], v[106:107], 0, v[150:151]
	v_cvt_pk_bf16_f32 v106, v118, v119
	v_cvt_pk_bf16_f32 v107, v120, v121
	v_cvt_pk_bf16_f32 v108, v110, v111
	v_cvt_pk_bf16_f32 v109, v112, v113
	v_subrev_u32_e32 v218, s12, v114
	global_store_dwordx4 v218, v[106:109], s[12:13] sc1
	v_cvt_pk_bf16_f32 v98, v98, v99
	v_cvt_pk_bf16_f32 v99, v100, v101
	v_cvt_pk_bf16_f32 v100, v90, v91
	v_or_b32_e32 v90, 32, v146
	v_ashrrev_i32_e32 v91, 31, v90
	v_lshlrev_b64 v[90:91], 11, v[90:91]
	v_lshl_add_u64 v[90:91], s[12:13], 0, v[90:91]
	v_cvt_pk_bf16_f32 v101, v92, v93
	v_subrev_u32_e32 v218, s12, v114
	global_store_dwordx4 v218, v[98:101], s[12:13] offset:256 sc1
	s_nop 1
	v_lshl_add_u64 v[98:99], v[90:91], 0, v[150:151]
	v_cvt_pk_bf16_f32 v90, v102, v103
	v_cvt_pk_bf16_f32 v91, v104, v105
	v_cvt_pk_bf16_f32 v92, v94, v95
	v_cvt_pk_bf16_f32 v93, v96, v97
	v_subrev_u32_e32 v218, s12, v98
	global_store_dwordx4 v218, v[90:93], s[12:13] sc1
	v_cvt_pk_bf16_f32 v82, v82, v83
	v_cvt_pk_bf16_f32 v83, v84, v85
	v_cvt_pk_bf16_f32 v84, v74, v75
	v_or_b32_e32 v74, 48, v146
	v_ashrrev_i32_e32 v75, 31, v74
	v_lshlrev_b64 v[74:75], 11, v[74:75]
	v_lshl_add_u64 v[74:75], s[12:13], 0, v[74:75]
	v_cvt_pk_bf16_f32 v85, v76, v77
	v_subrev_u32_e32 v218, s12, v98
	global_store_dwordx4 v218, v[82:85], s[12:13] offset:256 sc1
	s_nop 1
	v_lshl_add_u64 v[82:83], v[74:75], 0, v[150:151]
	v_cvt_pk_bf16_f32 v74, v86, v87
	v_cvt_pk_bf16_f32 v75, v88, v89
	v_cvt_pk_bf16_f32 v76, v78, v79
	v_cvt_pk_bf16_f32 v77, v80, v81
	v_subrev_u32_e32 v218, s12, v82
	global_store_dwordx4 v218, v[74:77], s[12:13] sc1
	v_cvt_pk_bf16_f32 v70, v70, v71
	v_cvt_pk_bf16_f32 v71, v72, v73
	v_cvt_pk_bf16_f32 v72, v66, v67
	v_cvt_pk_bf16_f32 v73, v68, v69
	v_subrev_u32_e32 v218, s12, v82
	global_store_dwordx4 v218, v[70:73], s[12:13] offset:256 sc1
	v_cvt_pk_bf16_f32 v62, v62, v63
	v_cvt_pk_bf16_f32 v63, v64, v65
	v_cvt_pk_bf16_f32 v64, v58, v59
	v_add_co_u32_e32 v58, vcc, s77, v140
	v_lshl_add_u64 v[66:67], v[140:141], 0, s[80:81]
	s_nop 0
	v_addc_co_u32_e32 v59, vcc, 0, v141, vcc
	v_cvt_pk_bf16_f32 v65, v60, v61
	v_subrev_u32_e32 v218, s12, v58
	global_store_dwordx4 v218, v[62:65], s[12:13] sc1
	v_cvt_pk_bf16_f32 v50, v50, v51
	v_cvt_pk_bf16_f32 v51, v52, v53
	v_cvt_pk_bf16_f32 v52, v42, v43
	v_cvt_pk_bf16_f32 v53, v44, v45
	v_subrev_u32_e32 v218, s12, v66
	global_store_dwordx4 v218, v[50:53], s[12:13] offset:256 sc1
	v_cvt_pk_bf16_f32 v42, v54, v55
	v_cvt_pk_bf16_f32 v43, v56, v57
	v_cvt_pk_bf16_f32 v44, v46, v47
	v_add_co_u32_e32 v46, vcc, s87, v140
	s_nop 0
	v_lshl_add_u64 v[50:51], v[140:141], 0, s[88:89]
	v_addc_co_u32_e32 v47, vcc, 0, v141, vcc
	v_cvt_pk_bf16_f32 v45, v48, v49
	v_subrev_u32_e32 v218, s12, v46
	global_store_dwordx4 v218, v[42:45], s[12:13] sc1
	v_cvt_pk_bf16_f32 v34, v34, v35
	v_cvt_pk_bf16_f32 v35, v36, v37
	v_cvt_pk_bf16_f32 v36, v26, v27
	v_cvt_pk_bf16_f32 v37, v28, v29
	v_subrev_u32_e32 v218, s12, v50
	global_store_dwordx4 v218, v[34:37], s[12:13] offset:256 sc1
	v_cvt_pk_bf16_f32 v26, v38, v39
	v_cvt_pk_bf16_f32 v27, v40, v41
	v_cvt_pk_bf16_f32 v28, v30, v31
	v_add_co_u32_e32 v30, vcc, s94, v140
	s_nop 0
	v_lshl_add_u64 v[34:35], v[140:141], 0, s[90:91]
	v_addc_co_u32_e32 v31, vcc, 0, v141, vcc
	v_cvt_pk_bf16_f32 v29, v32, v33
	v_subrev_u32_e32 v218, s12, v30
	global_store_dwordx4 v218, v[26:29], s[12:13] sc1
	v_cvt_pk_bf16_f32 v18, v18, v19
	v_cvt_pk_bf16_f32 v19, v20, v21
	v_cvt_pk_bf16_f32 v20, v10, v11
	v_cvt_pk_bf16_f32 v21, v12, v13
	v_subrev_u32_e32 v218, s12, v34
	global_store_dwordx4 v218, v[18:21], s[12:13] offset:256 sc1
	v_cvt_pk_bf16_f32 v10, v22, v23
	v_cvt_pk_bf16_f32 v11, v24, v25
	v_cvt_pk_bf16_f32 v12, v14, v15
	v_add_co_u32_e32 v14, vcc, s95, v140
	s_nop 0
	v_lshl_add_u64 v[18:19], v[140:141], 0, s[92:93]
	v_addc_co_u32_e32 v15, vcc, 0, v141, vcc
	s_and_b64 vcc, exec, s[6:7]
	s_mov_b64 s[6:7], -1
	v_cvt_pk_bf16_f32 v13, v16, v17
	v_subrev_u32_e32 v218, s12, v14
	global_store_dwordx4 v218, v[10:13], s[12:13] sc1
	v_cvt_pk_bf16_f32 v6, v6, v7
	v_cvt_pk_bf16_f32 v7, v8, v9
	v_cvt_pk_bf16_f32 v8, v2, v3
	v_cvt_pk_bf16_f32 v9, v4, v5
	v_subrev_u32_e32 v218, s12, v18
	global_store_dwordx4 v218, v[6:9], s[12:13] offset:256 sc1
	s_cbranch_vccnz .LBB0_691
	s_andn2_b64 vcc, exec, s[10:11]
	s_cbranch_vccnz .LBB0_690
	s_barrier
	s_branch .LBB0_690
